# v53 + attention: K staged two tiles ahead in a 3-slot LDS ring so wave group A also issues its next tile's first K-fragment reads before the barrier (read/write addresses stepped by SALU-computed delt
# baseline (speedup 1.0000x reference)
; __device__ __forceinline__ void unpack8(const u32x4 w, float* f) { f[0] = bf_lo(w.x); f[1] = bf_hi(w.x); f[2] = bf_lo(w.y); f[3] = bf_hi(w.y); f[4] = bf_lo(w.z); f[5] = bf_hi(w.z); f[6] = bf_lo(w.w); f[7] = bf_hi(w.w); }
; __device__ __forceinline__ void attn_unit(const bf16_t* __restrict__ Qb, const bf16_t* __restrict__ KV, const bf16_t* __restrict__ KP, bf16_t* __restrict__ Ob, ...
;     ...
;   float m_reg = -1e30f, l_reg = 0; f32x16 o[4] = {}; bf16x8 qr[12];
;   const bf16_t* Qw = Qb + (size_t)(qrow0 + wid * QBLK + r32) * LDQ + h * QKD + hi * 8;
; #pragma unroll
;   for (int d0 = 0; d0 < 12; ++d0) qr[d0] = ld8(Qw + d0 * 16);
;   {
;     float qf[12][8]; float ss = 0.f;
; #pragma unroll
;     for (int d0 = 0; d0 < 12; ++d0) { const u32x4 w = *reinterpret_cast<const u32x4*>(&qr[d0]); unpack8(w, qf[d0]);
; #pragma unroll
;       for (int jj = 0; jj < 8; ++jj) ss += qf[d0][jj] * qf[d0][jj]; }
;     { auto rr = __builtin_amdgcn_permlane32_swap(__float_as_uint(ss), __float_as_uint(ss), false, false); ss = __uint_as_float(rr[0]) + __uint_as_float(rr[1]); }
.LBB0_1452:
	s_ashr_i32 s8, s2, 7
	s_lshl_b32 s6, s2, 8
	v_mov_b32_e32 v162, v188
	s_lshl_b32 s24, s8, 12
	s_and_b32 s6, s6, 0xf00
	s_or_b32 s6, s24, s6
	v_ashrrev_i32_e32 v0, 1, v162
	v_and_b32_e32 v0, 0xffffffe0, v0
	v_and_b32_e32 v184, 31, v162
	v_add_u32_e32 v178, s6, v0
	s_bfe_u32 s3, s2, 0x30004
	v_or_b32_e32 v36, v178, v184
	v_mov_b64_e32 v[0:1], s[14:15]
	v_bfe_u32 v185, v162, 5, 1
	v_mad_i64_i32 v[0:1], s[6:7], v36, s89, v[0:1]
	s_mul_i32 s68, s3, 0x180
	v_lshl_add_u64 v[0:1], v[0:1], 0, s[68:69]
	v_lshlrev_b32_e32 v172, 4, v185
	v_lshl_add_u64 v[32:33], v[0:1], 0, v[172:173]
	global_load_dwordx4 v[20:23], v[32:33], off
	global_load_dwordx4 v[24:27], v[32:33], off offset:32
	global_load_dwordx4 v[16:19], v[32:33], off offset:64
	global_load_dwordx4 v[12:15], v[32:33], off offset:96
	global_load_dwordx4 v[8:11], v[32:33], off offset:128
	global_load_dwordx4 v[4:7], v[32:33], off offset:160
	global_load_dwordx4 v[0:3], v[32:33], off offset:192
	v_and_b32_e32 v124, 32, v162
	global_load_dwordx4 v[112:115], v124, s[20:21] offset:704
	global_load_dwordx4 v[138:141], v124, s[20:21] offset:720
	global_load_dwordx4 v[28:31], v[32:33], off offset:224
	global_load_dwordx4 v[100:103], v[32:33], off offset:256
	global_load_dwordx4 v[96:99], v[32:33], off offset:288
	global_load_dwordx4 v[116:119], v[32:33], off offset:320
	global_load_dwordx4 v[120:123], v[32:33], off offset:352
	v_mov_b32_e32 v125, v173
	s_mov_b64 s[6:7], 0x1000
	s_lshl_b32 s25, s8, 8
	s_add_i32 s11, 0, 0x14000
	s_add_i32 s31, s25, 0x4000
	s_cmp_lg_u32 0, -1
	s_cselect_b32 s34, 0, 0
	s_mov_b32 s50, s48
	s_mov_b32 s51, s48
	s_mov_b32 s52, s48
	s_mov_b32 s53, s48
	s_mov_b32 s54, s48
	s_mov_b32 s55, s48
	s_mov_b32 s56, s48
	s_mov_b32 s57, s48
	s_mov_b32 s58, s48
	s_mov_b32 s59, s48
	s_mov_b32 s60, s48
	s_mov_b32 s61, s48
	s_mov_b32 s62, s48
	s_mov_b32 s63, s48
	v_mov_b64_e32 v[190:191], 0x100
	v_mov_b64_e32 v[252:253], 0xff
	s_waitcnt vmcnt(0)
	v_lshlrev_b32_e32 v229, 16, v20
	v_and_b32_e32 v230, 0xffff0000, v20
	v_lshlrev_b32_e32 v214, 16, v16
	v_and_b32_e32 v213, 0xffff0000, v16
	v_lshlrev_b32_e32 v212, 16, v17
	v_and_b32_e32 v211, 0xffff0000, v17
	v_lshlrev_b32_e32 v210, 16, v18
	v_and_b32_e32 v209, 0xffff0000, v18
	v_lshlrev_b32_e32 v208, 16, v19
	v_and_b32_e32 v207, 0xffff0000, v19
	global_load_dwordx4 v[16:19], v124, s[20:21] offset:656
	v_lshlrev_b32_e32 v227, 16, v21
	v_and_b32_e32 v228, 0xffff0000, v21
	v_lshlrev_b32_e32 v225, 16, v22
	v_and_b32_e32 v226, 0xffff0000, v22
	v_lshlrev_b32_e32 v223, 16, v23
	v_and_b32_e32 v224, 0xffff0000, v23
	global_load_dwordx4 v[20:23], v124, s[20:21] offset:640
	v_mul_f32_e32 v194, v230, v230
	v_fmac_f32_e32 v194, v229, v229
	v_fmac_f32_e32 v194, v227, v227
	v_fmac_f32_e32 v194, v228, v228
	v_fmac_f32_e32 v194, v225, v225
	v_fmac_f32_e32 v194, v226, v226
	v_fmac_f32_e32 v194, v223, v223
	v_lshlrev_b32_e32 v221, 16, v24
	v_fmac_f32_e32 v194, v224, v224
	v_and_b32_e32 v222, 0xffff0000, v24
	v_fmac_f32_e32 v194, v221, v221
	v_lshlrev_b32_e32 v219, 16, v25
	v_fmac_f32_e32 v194, v222, v222
	v_and_b32_e32 v220, 0xffff0000, v25
	v_fmac_f32_e32 v194, v219, v219
	v_lshlrev_b32_e32 v218, 16, v26
	v_fmac_f32_e32 v194, v220, v220
	v_and_b32_e32 v217, 0xffff0000, v26
	v_fmac_f32_e32 v194, v218, v218
	v_lshlrev_b32_e32 v216, 16, v27
	v_fmac_f32_e32 v194, v217, v217
	v_and_b32_e32 v215, 0xffff0000, v27
	v_fmac_f32_e32 v194, v216, v216
	v_fmac_f32_e32 v194, v215, v215
	v_fmac_f32_e32 v194, v214, v214
	v_fmac_f32_e32 v194, v213, v213
	v_fmac_f32_e32 v194, v212, v212
	v_fmac_f32_e32 v194, v211, v211
	v_fmac_f32_e32 v194, v210, v210
	v_lshlrev_b32_e32 v165, 16, v0
	v_and_b32_e32 v164, 0xffff0000, v0
	v_fmac_f32_e32 v194, v209, v209
	v_lshlrev_b32_e32 v0, 6, v36
	v_lshlrev_b32_e32 v163, 16, v1
	v_fmac_f32_e32 v194, v208, v208
	v_and_b32_e32 v239, 0xffff0000, v1
	v_lshl_add_u64 v[24:25], s[18:19], 0, v[124:125]
	v_and_b32_e32 v0, 0xfc0, v0
	v_mov_b32_e32 v1, v173
	v_lshlrev_b32_e32 v206, 16, v12
	v_lshlrev_b32_e32 v180, 16, v4
	v_and_b32_e32 v179, 0xffff0000, v4
	v_lshlrev_b32_e32 v171, 16, v5
	v_and_b32_e32 v170, 0xffff0000, v5
	v_fmac_f32_e32 v194, v207, v207
	v_lshl_add_u64 v[4:5], v[24:25], 0, v[0:1]
	v_and_b32_e32 v205, 0xffff0000, v12
	v_lshlrev_b32_e32 v198, 16, v8
	v_and_b32_e32 v197, 0xffff0000, v8
	v_lshlrev_b32_e32 v196, 16, v9
	v_and_b32_e32 v187, 0xffff0000, v9
	v_lshlrev_b32_e32 v186, 16, v10
	v_and_b32_e32 v183, 0xffff0000, v10
	v_lshlrev_b32_e32 v182, 16, v11
	v_and_b32_e32 v181, 0xffff0000, v11
	v_lshlrev_b32_e32 v169, 16, v6
	v_and_b32_e32 v168, 0xffff0000, v6
	v_lshlrev_b32_e32 v167, 16, v7
	v_and_b32_e32 v166, 0xffff0000, v7
	v_fmac_f32_e32 v194, v206, v206
	v_lshlrev_b32_e32 v237, 16, v2
	v_and_b32_e32 v235, 0xffff0000, v2
	v_lshlrev_b32_e32 v233, 16, v3
	v_and_b32_e32 v231, 0xffff0000, v3
	global_load_dwordx4 v[104:107], v124, s[20:21] offset:16
	global_load_dwordx4 v[108:111], v124, s[20:21]
	global_load_dwordx4 v[88:91], v124, s[20:21] offset:80
	global_load_dwordx4 v[92:95], v124, s[20:21] offset:64
	global_load_dwordx4 v[80:83], v124, s[20:21] offset:144
	global_load_dwordx4 v[84:87], v124, s[20:21] offset:128
	global_load_dwordx4 v[72:75], v124, s[20:21] offset:208
	global_load_dwordx4 v[76:79], v124, s[20:21] offset:192
	global_load_dwordx4 v[64:67], v124, s[20:21] offset:272
	global_load_dwordx4 v[68:71], v124, s[20:21] offset:256
	global_load_dwordx4 v[48:51], v124, s[20:21] offset:336
	global_load_dwordx4 v[56:59], v124, s[20:21] offset:320
	global_load_dwordx4 v[32:35], v124, s[20:21] offset:400
	global_load_dwordx4 v[40:43], v124, s[20:21] offset:384
	global_load_dwordx4 v[8:11], v[4:5], off
	global_load_dwordx4 v[0:3], v[4:5], off offset:16
; __device__ __forceinline__ void unpack8(const u32x4 w, float* f) { f[0] = bf_lo(w.x); f[1] = bf_hi(w.x); f[2] = bf_lo(w.y); f[3] = bf_hi(w.y); f[4] = bf_lo(w.z); f[5] = bf_hi(w.z); f[6] = bf_lo(w.w); f[7] = bf_hi(w.w); }
; __device__ __forceinline__ void attn_unit(const bf16_t* __restrict__ Qb, const bf16_t* __restrict__ KV, const bf16_t* __restrict__ KP, bf16_t* __restrict__ Ob, ...
;     ...
;     float qf[12][8]; float ss = 0.f;
; #pragma unroll
;     for (int d0 = 0; d0 < 12; ++d0) { const u32x4 w = *reinterpret_cast<const u32x4*>(&qr[d0]); unpack8(w, qf[d0]);
; #pragma unroll
;       for (int jj = 0; jj < 8; ++jj) ss += qf[d0][jj] * qf[d0][jj]; }
;     { auto rr = __builtin_amdgcn_permlane32_swap(__float_as_uint(ss), __float_as_uint(ss), false, false); ss = __uint_as_float(rr[0]) + __uint_as_float(rr[1]); }
;     ...
;     if (do_rope) { const int s = (qrow0 + wid * QBLK + r32) & (SEQ - 1), pr_ = s >> 6, pc_ = s & 63;
; #pragma unroll
;       for (int ax = 0; ax < 2; ++ax) { const float* cp = rope + (ax ? pc_ : pr_) * 16 + hi * 8; const f32x4 c0 = *(const f32x4*)cp, c1 = *(const f32x4*)(cp + 4), s0 = *(const f32x4*)(cp + 1024), s1 = *(const f32x4*)(cp + 1028);
	v_lshl_add_u64 v[6:7], v[4:5], 0, s[6:7]
	v_add_co_u32_e32 v4, vcc, s49, v4
	v_lshlrev_b32_e32 v204, 16, v13
	v_fmac_f32_e32 v194, v205, v205
	v_addc_co_u32_e32 v5, vcc, 0, v5, vcc
	v_and_b32_e32 v203, 0xffff0000, v13
	v_lshlrev_b32_e32 v202, 16, v14
	v_and_b32_e32 v201, 0xffff0000, v14
	v_lshlrev_b32_e32 v200, 16, v15
	v_and_b32_e32 v199, 0xffff0000, v15
	v_fmac_f32_e32 v194, v204, v204
	v_lshlrev_b32_e32 v241, 16, v28
	v_and_b32_e32 v244, 0xffff0000, v28
	v_lshlrev_b32_e32 v245, 16, v29
	v_and_b32_e32 v240, 0xffff0000, v29
	v_lshlrev_b32_e32 v238, 16, v30
	v_and_b32_e32 v236, 0xffff0000, v30
	v_lshlrev_b32_e32 v234, 16, v31
	v_and_b32_e32 v232, 0xffff0000, v31
	global_load_dwordx4 v[12:15], v[4:5], off
	s_nop 0
	global_load_dwordx4 v[4:7], v[6:7], off offset:16
	s_nop 0
	global_load_dwordx4 v[52:55], v124, s[20:21] offset:464
	global_load_dwordx4 v[60:63], v124, s[20:21] offset:448
	global_load_dwordx4 v[36:39], v124, s[20:21] offset:512
	global_load_dwordx4 v[28:31], v124, s[20:21] offset:528
	global_load_dwordx4 v[44:47], v124, s[20:21] offset:576
	s_nop 0
	global_load_dwordx4 v[124:127], v124, s[20:21] offset:592
	v_fmac_f32_e32 v194, v203, v203
	v_fmac_f32_e32 v194, v202, v202
	v_fmac_f32_e32 v194, v201, v201
	v_fmac_f32_e32 v194, v200, v200
	v_fmac_f32_e32 v194, v199, v199
	v_fmac_f32_e32 v194, v198, v198
	v_fmac_f32_e32 v194, v197, v197
	v_fmac_f32_e32 v194, v196, v196
	v_fmac_f32_e32 v194, v187, v187
	v_fmac_f32_e32 v194, v186, v186
	v_fmac_f32_e32 v194, v183, v183
	v_fmac_f32_e32 v194, v182, v182
	v_fmac_f32_e32 v194, v181, v181
	v_fmac_f32_e32 v194, v180, v180
	v_fmac_f32_e32 v194, v179, v179
	v_fmac_f32_e32 v194, v171, v171
	v_fmac_f32_e32 v194, v170, v170
	v_fmac_f32_e32 v194, v169, v169
	v_fmac_f32_e32 v194, v168, v168
	v_fmac_f32_e32 v194, v167, v167
	v_fmac_f32_e32 v194, v166, v166
	v_fmac_f32_e32 v194, v165, v165
	v_fmac_f32_e32 v194, v164, v164
	v_fmac_f32_e32 v194, v163, v163
	v_fmac_f32_e32 v194, v239, v239
	v_fmac_f32_e32 v194, v237, v237
	v_fmac_f32_e32 v194, v235, v235
	v_fmac_f32_e32 v194, v233, v233
	v_fmac_f32_e32 v194, v231, v231
	v_fmac_f32_e32 v194, v241, v241
	v_fmac_f32_e32 v194, v244, v244
	v_fmac_f32_e32 v194, v245, v245
	v_fmac_f32_e32 v194, v240, v240
	v_fmac_f32_e32 v194, v238, v238
	v_fmac_f32_e32 v194, v236, v236
	v_fmac_f32_e32 v194, v234, v234
	v_lshlrev_b32_e32 v159, 16, v100
	v_lshlrev_b32_e32 v158, 16, v96
	v_fmac_f32_e32 v194, v232, v232
	v_lshlrev_b32_e32 v154, 16, v97
	v_and_b32_e32 v156, 0xffff0000, v97
	v_and_b32_e32 v161, 0xffff0000, v100
	v_and_b32_e32 v160, 0xffff0000, v96
	v_pk_mul_f32 v[96:97], v[158:159], v[158:159]
	v_lshlrev_b32_e32 v146, 16, v99
	v_and_b32_e32 v148, 0xffff0000, v99
	v_lshlrev_b32_e32 v150, 16, v98
	v_and_b32_e32 v152, 0xffff0000, v98
	v_lshlrev_b32_e32 v155, 16, v101
	v_add_f32_e32 v97, v97, v194
	v_pk_mul_f32 v[98:99], v[160:161], v[160:161]
	v_pk_mul_f32 v[192:193], v[154:155], v[154:155]
	v_and_b32_e32 v157, 0xffff0000, v101
	v_add_f32_e32 v97, v99, v97
	v_lshlrev_b32_e32 v151, 16, v102
	v_pk_mul_f32 v[100:101], v[156:157], v[156:157]
	v_add_f32_e32 v97, v193, v97
	v_lshlrev_b32_e32 v128, 16, v123
	v_lshlrev_b32_e32 v129, 16, v119
	v_mov_b32_e32 v130, v140
	s_waitcnt vmcnt(25)
	v_mov_b32_e32 v131, v18
	v_and_b32_e32 v133, 0xffff0000, v119
	v_and_b32_e32 v132, 0xffff0000, v123
	v_mov_b32_e32 v18, v141
	v_lshlrev_b32_e32 v135, 16, v118
	v_lshlrev_b32_e32 v134, 16, v122
	v_and_b32_e32 v119, 0xffff0000, v118
	v_and_b32_e32 v118, 0xffff0000, v122
	v_lshlrev_b32_e32 v123, 16, v117
	v_lshlrev_b32_e32 v122, 16, v121
	v_and_b32_e32 v141, 0xffff0000, v117
	v_and_b32_e32 v140, 0xffff0000, v121
	v_lshlrev_b32_e32 v143, 16, v116
	v_lshlrev_b32_e32 v142, 16, v120
	v_and_b32_e32 v117, 0xffff0000, v116
	v_and_b32_e32 v116, 0xffff0000, v120
	v_pk_mul_f32 v[120:121], v[150:151], v[150:151]
	v_and_b32_e32 v153, 0xffff0000, v102
	v_add_f32_e32 v97, v101, v97
	v_lshlrev_b32_e32 v147, 16, v103
	v_and_b32_e32 v149, 0xffff0000, v103
	v_pk_mul_f32 v[102:103], v[152:153], v[152:153]
	v_add_f32_e32 v97, v121, v97
	v_mov_b32_e32 v144, v112
	s_waitcnt vmcnt(24)
	v_mov_b32_e32 v145, v20
	v_mov_b32_e32 v20, v113
	v_pk_mul_f32 v[112:113], v[146:147], v[146:147]
	v_add_f32_e32 v97, v103, v97
	v_mov_b32_e32 v136, v138
	v_mov_b32_e32 v137, v16
	v_mov_b32_e32 v16, v139
	v_mov_b32_e32 v138, v114
	v_mov_b32_e32 v139, v22
	v_mov_b32_e32 v22, v115
	v_pk_mul_f32 v[114:115], v[148:149], v[148:149]
	v_add_f32_e32 v97, v113, v97
	v_add_f32_e32 v97, v115, v97
	v_add_f32_e32 v96, v96, v97
	v_add_f32_e32 v101, v98, v96
	v_add_f32_e32 v101, v192, v101
	v_add_f32_e32 v100, v100, v101
	v_add_f32_e32 v100, v120, v100
	v_add_f32_e32 v100, v102, v100
	v_add_f32_e32 v102, v112, v100
	v_pk_mul_f32 v[100:101], v[142:143], v[142:143]
	v_add_f32_e32 v102, v114, v102
	v_and_b32_e32 v26, 0xfc0, v178
	v_mov_b32_e32 v27, v173
	v_pk_mul_f32 v[112:113], v[116:117], v[116:117]
	v_add_f32_e32 v101, v101, v102
	v_lshl_add_u64 v[174:175], v[24:25], 0, v[26:27]
	v_pk_mul_f32 v[120:121], v[122:123], v[122:123]
	v_add_f32_e32 v101, v113, v101
	v_lshl_add_u64 v[176:177], v[174:175], 0, s[6:7]
	v_pk_mul_f32 v[242:243], v[140:141], v[140:141]
	v_add_f32_e32 v101, v121, v101
	global_load_dwordx4 v[96:99], v[176:177], off offset:16
	v_pk_mul_f32 v[176:177], v[134:135], v[134:135]
	v_add_f32_e32 v101, v243, v101
	v_pk_mul_f32 v[192:193], v[118:119], v[118:119]
	v_add_f32_e32 v101, v177, v101
	v_add_f32_e32 v101, v193, v101
	v_fmac_f32_e32 v101, v129, v129
	v_fmac_f32_e32 v101, v133, v133
	v_add_f32_e32 v113, v100, v101
	v_add_f32_e32 v121, v112, v113
	global_load_dwordx4 v[24:27], v[174:175], off offset:16
	global_load_dwordx4 v[100:103], v[174:175], off
	v_add_co_u32_e32 v194, vcc, s49, v174
	v_add_f32_e32 v174, v120, v121
	s_nop 0
	v_addc_co_u32_e32 v195, vcc, 0, v175, vcc
	v_add_f32_e32 v177, v242, v174
	global_load_dwordx4 v[112:115], v[194:195], off
	v_mov_b32_e32 v174, v132
	v_mov_b32_e32 v175, v128
	v_add_f32_e32 v176, v176, v177
	v_pk_mul_f32 v[174:175], v[174:175], v[174:175]
	v_add_f32_e32 v176, v192, v176
	v_add_f32_e32 v175, v175, v176
	v_add_f32_e32 v174, v174, v175
	v_mov_b32_e32 v175, v174
	s_nop 1
	v_permlane32_swap_b32_e32 v174, v175
	v_add_f32_e32 v174, v174, v175
	v_fmamk_f32 v174, v174, 0x3baaaaab, v189
	v_mul_f32_e32 v175, 0x4f800000, v174
	v_cmp_gt_f32_e32 vcc, s91, v174
	s_waitcnt vmcnt(12)
; __device__ __forceinline__ void attn_unit(const bf16_t* __restrict__ Qb, const bf16_t* __restrict__ KV, const bf16_t* __restrict__ KP, bf16_t* __restrict__ Ob, ...
;     ...
;     const float rinv = 1.0f / sqrtf(ss * (1.f / QKD) + EPS);
; #pragma unroll
;     for (int d0 = 0; d0 < 12; ++d0) { const f32x4 g0 = *(const f32x4*)(qn + d0 * 16 + hi * 8), g1 = *(const f32x4*)(qn + d0 * 16 + hi * 8 + 4);
; #pragma unroll
;       for (int jj = 0; jj < 8; ++jj) qf[d0][jj] *= rinv * (jj < 4 ? g0[jj & 3] : g1[jj & 3]); }
	v_mov_b32_e32 v120, v2
	s_waitcnt vmcnt(10)
	v_mov_b32_e32 v121, v6
	v_cndmask_b32_e32 v176, v174, v175, vcc
	v_sqrt_f32_e32 v177, v176
	s_waitcnt vmcnt(4)
	v_mov_b32_e32 v174, v126
	v_mov_b32_e32 v175, v30
	v_mov_b32_e32 v30, v127
	v_add_u32_e32 v126, -1, v177
	v_fma_f32 v127, -v126, v177, v176
	v_cmp_ge_f32_e64 s[6:7], 0, v127
	v_add_u32_e32 v127, 1, v177
	s_mov_b32 s49, s48
	v_cndmask_b32_e64 v126, v177, v126, s[6:7]
	v_fma_f32 v177, -v127, v177, v176
	v_cmp_lt_f32_e64 s[6:7], 0, v177
	s_nop 1
	v_cndmask_b32_e64 v126, v126, v127, s[6:7]
	v_mul_f32_e32 v127, 0x37800000, v126
	v_cndmask_b32_e32 v126, v126, v127, vcc
	v_cmp_class_f32_e32 vcc, v176, v254
	v_mov_b32_e32 v127, v28
	v_mov_b32_e32 v28, v125
	v_cndmask_b32_e32 v176, v126, v176, vcc
	v_div_scale_f32 v177, s[6:7], v176, v176, 1.0
	v_rcp_f32_e32 v192, v177
	v_mov_b32_e32 v126, v124
	v_mov_b32_e32 v124, v0
	v_mov_b32_e32 v125, v4
	v_fma_f32 v193, -v177, v192, 1.0
	v_fmac_f32_e32 v192, v193, v192
	v_div_scale_f32 v193, vcc, 1.0, v176, 1.0
	v_mul_f32_e32 v194, v193, v192
	v_fma_f32 v195, -v177, v194, v193
	v_fmac_f32_e32 v194, v195, v192
	v_fma_f32 v177, -v177, v194, v193
	v_div_fmas_f32 v177, v177, v192, v194
	v_div_fixup_f32 v176, v177, v176, 1.0
	v_mul_f32_e32 v176, 0x3dd53b94, v176
	v_mul_f32_e32 v109, v109, v176
	v_mul_f32_e32 v230, v109, v230
	v_mov_b32_e32 v109, v38
	v_mov_b32_e32 v38, v47
	v_mov_b32_e32 v47, v36
	v_mul_f32_e32 v36, v88, v176
	v_mul_f32_e32 v218, v36, v218
	v_mul_f32_e32 v36, v89, v176
	v_mul_f32_e32 v217, v36, v217
	v_mul_f32_e32 v36, v90, v176
	v_mul_f32_e32 v90, v36, v216
	v_mul_f32_e32 v36, v91, v176
	v_mul_f32_e32 v91, v36, v215
	v_mul_f32_e32 v36, v84, v176
	v_mul_f32_e32 v84, v36, v214
	v_mul_f32_e32 v36, v85, v176
	v_mul_f32_e32 v85, v36, v213
	v_mul_f32_e32 v36, v86, v176
	v_mul_f32_e32 v86, v36, v212
	v_mul_f32_e32 v36, v87, v176
	v_mul_f32_e32 v87, v36, v211
	v_mul_f32_e32 v36, v176, v80
	v_mul_f32_e32 v80, v36, v210
	v_mul_f32_e32 v36, v176, v81
	v_mul_f32_e32 v81, v36, v209
	v_mul_f32_e32 v36, v176, v82
	v_mul_f32_e32 v82, v36, v208
	v_mul_f32_e32 v36, v176, v83
	v_mul_f32_e32 v83, v36, v207
	v_mul_f32_e32 v36, v176, v76
	v_mul_f32_e32 v76, v36, v206
	v_mul_f32_e32 v36, v176, v77
	v_mul_f32_e32 v77, v36, v205
	v_mul_f32_e32 v36, v176, v78
	v_mul_f32_e32 v78, v36, v204
	v_mul_f32_e32 v36, v176, v79
	v_mul_f32_e32 v79, v36, v203
	v_mul_f32_e32 v36, v176, v72
	v_mul_f32_e32 v72, v36, v202
	v_mul_f32_e32 v36, v176, v73
	v_mul_f32_e32 v73, v36, v201
	v_mul_f32_e32 v36, v176, v74
	v_mul_f32_e32 v74, v36, v200
	v_mul_f32_e32 v36, v176, v75
	v_mul_f32_e32 v75, v36, v199
	v_mul_f32_e32 v36, v176, v68
	v_mul_f32_e32 v68, v36, v198
	v_mul_f32_e32 v36, v176, v69
	v_mul_f32_e32 v69, v36, v197
	v_mul_f32_e32 v36, v176, v70
	v_mul_f32_e32 v70, v36, v196
	v_mul_f32_e32 v36, v176, v71
	v_mul_f32_e32 v71, v36, v187
	v_mul_f32_e32 v36, v176, v64
	v_mul_f32_e32 v64, v36, v186
	v_mul_f32_e32 v36, v176, v65
	v_mul_f32_e32 v65, v36, v183
	v_mul_f32_e32 v36, v176, v66
	v_mul_f32_e32 v66, v36, v182
	v_mul_f32_e32 v36, v176, v67
	v_mul_f32_e32 v67, v36, v181
	v_mul_f32_e32 v36, v176, v56
	v_mul_f32_e32 v56, v36, v180
	v_mul_f32_e32 v36, v176, v57
	v_mul_f32_e32 v57, v36, v179
	v_mul_f32_e32 v36, v176, v58
	v_mul_f32_e32 v32, v176, v32
	v_mul_f32_e32 v58, v36, v171
	v_mul_f32_e32 v171, v32, v237
	v_mul_f32_e32 v32, v176, v33
	v_mul_f32_e32 v179, v32, v235
	v_mul_f32_e32 v32, v176, v34
	v_mul_f32_e32 v36, v176, v59
	v_mul_f32_e32 v180, v32, v233
	v_mul_f32_e32 v32, v176, v35
	v_mul_f32_e32 v59, v36, v170
	v_mul_f32_e32 v36, v176, v48
	v_mul_f32_e32 v181, v32, v231
	v_mul_f32_e32 v32, v176, v60
	v_mul_f32_e32 v169, v36, v169
	v_mul_f32_e32 v36, v176, v49
	v_mul_f32_e32 v60, v32, v241
	v_mul_f32_e32 v32, v176, v61
	v_mul_f32_e32 v168, v36, v168
	v_mul_f32_e32 v36, v176, v50
	v_mul_f32_e32 v61, v32, v244
	v_mul_f32_e32 v32, v176, v62
	v_mul_f32_e32 v167, v36, v167
	v_mul_f32_e32 v36, v176, v51
	v_mul_f32_e32 v62, v32, v245
	v_mul_f32_e32 v32, v176, v63
	v_mul_f32_e32 v166, v36, v166
	v_mul_f32_e32 v36, v176, v40
	v_mul_f32_e32 v63, v32, v240
	v_mul_f32_e32 v32, v176, v52
	v_mul_f32_e32 v165, v36, v165
	v_mul_f32_e32 v36, v176, v41
	v_mul_f32_e32 v182, v32, v238
	v_mul_f32_e32 v32, v176, v53
	v_mul_f32_e32 v108, v108, v176
	v_mul_f32_e32 v177, v104, v176
	v_mul_f32_e32 v164, v36, v164
	v_mul_f32_e32 v36, v176, v42
	v_mul_f32_e32 v183, v32, v236
	v_mul_f32_e32 v32, v176, v54
	v_mul_f32_e32 v229, v108, v229
	v_mul_f32_e32 v177, v177, v225
	v_mov_b32_e32 v108, v46
	v_mov_b32_e32 v46, v44
	v_mul_f32_e32 v163, v36, v163
	v_mul_f32_e32 v36, v176, v43
	v_mul_f32_e32 v54, v32, v234
	v_mul_f32_e32 v32, v176, v55
	v_mul_f32_e32 v170, v36, v239
	v_mul_f32_e32 v55, v32, v232
	v_pk_mul_f32 v[32:33], v[176:177], v[46:47] op_sel_hi:[0,1]
	v_mov_b32_e32 v36, v45
	s_waitcnt vmcnt(1)
	v_mov_b32_e32 v88, v100
	s_waitcnt vmcnt(0)
; __device__ __forceinline__ void attn_unit(const bf16_t* __restrict__ Qb, const bf16_t* __restrict__ KV, const bf16_t* __restrict__ KP, bf16_t* __restrict__ Ob, ...
;     ...
;     if (do_rope) { const int s = (qrow0 + wid * QBLK + r32) & (SEQ - 1), pr_ = s >> 6, pc_ = s & 63;
; #pragma unroll
;       for (int ax = 0; ax < 2; ++ax) { const float* cp = rope + (ax ? pc_ : pr_) * 16 + hi * 8; const f32x4 c0 = *(const f32x4*)cp, c1 = *(const f32x4*)(cp + 4), s0 = *(const f32x4*)(cp + 1024), s1 = *(const f32x4*)(cp + 1028);
; #pragma unroll
;         for (int jj = 0; jj < 8; ++jj) { const float c = jj < 4 ? c0[jj & 3] : c1[jj & 3], sn = jj < 4 ? s0[jj & 3] : s1[jj & 3], a = qf[8 + 2 * ax][jj], b = qf[9 + 2 * ax][jj];
;           qf[8 + 2 * ax][jj] = a * c - b * sn; qf[9 + 2 * ax][jj] = b * c + a * sn; } } }
	v_mov_b32_e32 v89, v112
	v_pk_mul_f32 v[32:33], v[32:33], v[158:159]
	v_pk_mul_f32 v[34:35], v[176:177], v[36:37] op_sel_hi:[0,1]
	v_mov_b32_e32 v52, v112
	v_mov_b32_e32 v53, v100
	v_pk_mul_f32 v[34:35], v[34:35], v[160:161]
	v_pk_mul_f32 v[52:53], v[32:33], v[52:53]
	v_pk_mul_f32 v[32:33], v[32:33], v[88:89]
	v_mov_b32_e32 v100, v113
	v_sub_f32_e32 v52, v53, v52
	v_add_f32_e32 v53, v32, v33
	v_pk_mul_f32 v[32:33], v[34:35], v[100:101]
	v_mov_b32_e32 v112, v101
	v_pk_mul_f32 v[36:37], v[176:177], v[108:109] op_sel_hi:[0,1]
	v_sub_f32_e32 v88, v33, v32
	v_pk_mul_f32 v[32:33], v[34:35], v[112:113]
	v_mul_f32_e32 v110, v110, v176
	v_mul_f32_e32 v111, v111, v176
	v_pk_mul_f32 v[36:37], v[36:37], v[154:155]
	v_add_f32_e32 v34, v32, v33
	v_mov_b32_e32 v32, v114
	v_mov_b32_e32 v33, v102
	v_mul_f32_e32 v227, v110, v227
	v_mul_f32_e32 v228, v111, v228
	v_mov_b32_e32 v110, v102
	v_mov_b32_e32 v111, v114
	v_pk_mul_f32 v[38:39], v[176:177], v[38:39] op_sel_hi:[0,1]
	v_pk_mul_f32 v[32:33], v[36:37], v[32:33]
	v_pk_mul_f32 v[38:39], v[38:39], v[156:157]
	v_sub_f32_e32 v35, v33, v32
	v_pk_mul_f32 v[32:33], v[36:37], v[110:111]
	v_mov_b32_e32 v102, v115
	v_add_f32_e32 v36, v32, v33
	v_pk_mul_f32 v[32:33], v[38:39], v[102:103]
	v_mov_b32_e32 v114, v103
	v_pk_mul_f32 v[40:41], v[176:177], v[126:127] op_sel_hi:[0,1]
	v_sub_f32_e32 v37, v33, v32
	v_pk_mul_f32 v[32:33], v[38:39], v[114:115]
	v_pk_mul_f32 v[40:41], v[40:41], v[150:151]
	v_add_f32_e32 v38, v32, v33
	v_mov_b32_e32 v32, v96
	v_mov_b32_e32 v33, v24
	v_mul_f32_e32 v193, v106, v176
	v_mul_f32_e32 v194, v107, v176
	v_mov_b32_e32 v106, v24
	v_mov_b32_e32 v107, v96
	v_pk_mul_f32 v[28:29], v[176:177], v[28:29] op_sel_hi:[0,1]
	v_pk_mul_f32 v[32:33], v[40:41], v[32:33]
	v_pk_mul_f32 v[28:29], v[28:29], v[152:153]
	v_sub_f32_e32 v39, v33, v32
	v_pk_mul_f32 v[32:33], v[40:41], v[106:107]
	v_mov_b32_e32 v24, v97
	v_mov_b32_e32 v96, v25
	v_pk_mul_f32 v[42:43], v[176:177], v[174:175] op_sel_hi:[0,1]
	v_add_f32_e32 v40, v32, v33
	v_pk_mul_f32 v[32:33], v[28:29], v[24:25]
	v_pk_mul_f32 v[24:25], v[28:29], v[96:97]
	v_pk_mul_f32 v[42:43], v[42:43], v[146:147]
	v_add_f32_e32 v28, v24, v25
	v_mov_b32_e32 v24, v98
	v_mov_b32_e32 v25, v26
	v_mul_f32_e32 v192, v105, v176
	v_mov_b32_e32 v104, v26
	v_mov_b32_e32 v105, v98
	v_pk_mul_f32 v[30:31], v[176:177], v[30:31] op_sel_hi:[0,1]
	v_pk_mul_f32 v[24:25], v[42:43], v[24:25]
	v_pk_mul_f32 v[30:31], v[30:31], v[148:149]
	v_sub_f32_e32 v29, v25, v24
	v_pk_mul_f32 v[24:25], v[42:43], v[104:105]
	v_mov_b32_e32 v26, v99
	v_sub_f32_e32 v32, v33, v32
	v_add_f32_e32 v33, v24, v25
	v_pk_mul_f32 v[24:25], v[30:31], v[26:27]
	v_mov_b32_e32 v98, v27
	v_pk_mul_f32 v[44:45], v[176:177], v[144:145] op_sel_hi:[0,1]
	v_sub_f32_e32 v26, v25, v24
	v_pk_mul_f32 v[24:25], v[30:31], v[98:99]
	v_pk_mul_f32 v[44:45], v[44:45], v[142:143]
	v_add_f32_e32 v27, v24, v25
	v_mov_b32_e32 v24, v12
	v_mov_b32_e32 v25, v8
	v_mul_f32_e32 v243, v94, v176
	v_mul_f32_e32 v246, v95, v176
	v_mov_b32_e32 v94, v8
	v_mov_b32_e32 v95, v12
	v_pk_mul_f32 v[20:21], v[176:177], v[20:21] op_sel_hi:[0,1]
	v_pk_mul_f32 v[24:25], v[44:45], v[24:25]
	v_pk_mul_f32 v[20:21], v[20:21], v[116:117]
	v_sub_f32_e32 v30, v25, v24
	v_pk_mul_f32 v[24:25], v[44:45], v[94:95]
	v_mov_b32_e32 v8, v13
	v_mov_b32_e32 v12, v9
	v_pk_mul_f32 v[46:47], v[176:177], v[138:139] op_sel_hi:[0,1]
	v_add_f32_e32 v31, v24, v25
	v_pk_mul_f32 v[24:25], v[20:21], v[8:9]
	v_pk_mul_f32 v[8:9], v[20:21], v[12:13]
	v_pk_mul_f32 v[46:47], v[46:47], v[122:123]
	v_add_f32_e32 v12, v8, v9
	v_mov_b32_e32 v8, v14
	v_mov_b32_e32 v9, v10
	v_mul_f32_e32 v195, v92, v176
	v_mul_f32_e32 v242, v93, v176
	v_mov_b32_e32 v92, v10
	v_mov_b32_e32 v93, v14
	v_pk_mul_f32 v[22:23], v[176:177], v[22:23] op_sel_hi:[0,1]
	v_pk_mul_f32 v[8:9], v[46:47], v[8:9]
	v_pk_mul_f32 v[22:23], v[22:23], v[140:141]
	v_sub_f32_e32 v13, v9, v8
	v_pk_mul_f32 v[8:9], v[46:47], v[92:93]
	v_mov_b32_e32 v10, v15
	v_add_f32_e32 v20, v8, v9
	v_pk_mul_f32 v[8:9], v[22:23], v[10:11]
	v_mov_b32_e32 v14, v11
	v_pk_mul_f32 v[48:49], v[176:177], v[136:137] op_sel_hi:[0,1]
	v_sub_f32_e32 v10, v9, v8
	v_pk_mul_f32 v[8:9], v[22:23], v[14:15]
	v_pk_mul_f32 v[48:49], v[48:49], v[134:135]
	v_add_f32_e32 v11, v8, v9
	v_mov_b32_e32 v8, v4
	v_mov_b32_e32 v9, v0
	v_pk_mul_f32 v[16:17], v[176:177], v[16:17] op_sel_hi:[0,1]
	v_pk_mul_f32 v[8:9], v[48:49], v[8:9]
	v_pk_mul_f32 v[16:17], v[16:17], v[118:119]
	v_sub_f32_e32 v14, v9, v8
	v_pk_mul_f32 v[8:9], v[48:49], v[124:125]
	v_mov_b32_e32 v0, v5
	v_mov_b32_e32 v4, v1
	v_pk_mul_f32 v[50:51], v[176:177], v[130:131] op_sel_hi:[0,1]
	v_add_f32_e32 v15, v8, v9
	v_pk_mul_f32 v[8:9], v[16:17], v[0:1]
	v_pk_mul_f32 v[0:1], v[16:17], v[4:5]
	v_pk_mul_f32 v[50:51], v[50:51], v[128:129]
	v_add_f32_e32 v4, v0, v1
	v_mov_b32_e32 v0, v6
	v_mov_b32_e32 v1, v2
	v_pk_mul_f32 v[18:19], v[176:177], v[18:19] op_sel_hi:[0,1]
	v_pk_mul_f32 v[0:1], v[50:51], v[0:1]
	v_pk_mul_f32 v[18:19], v[18:19], v[132:133]
	v_sub_f32_e32 v5, v1, v0
	v_pk_mul_f32 v[0:1], v[50:51], v[120:121]
	v_mov_b32_e32 v2, v7
	v_sub_f32_e32 v8, v9, v8
	v_add_f32_e32 v9, v0, v1
	v_pk_mul_f32 v[0:1], v[18:19], v[2:3]
	v_mov_b32_e32 v6, v3
	v_sub_f32_e32 v2, v1, v0
	v_pk_mul_f32 v[0:1], v[18:19], v[6:7]
	v_mul_f32_e32 v192, v192, v226
	v_mul_f32_e32 v193, v193, v223
	v_mul_f32_e32 v194, v194, v224
	v_mul_f32_e32 v195, v195, v221
	v_mul_f32_e32 v221, v242, v222
	v_mul_f32_e32 v219, v243, v219
	v_mul_f32_e32 v220, v246, v220
	v_add_f32_e32 v0, v0, v1
	v_cvt_pk_bf16_f32 v136, v229, v230
	v_cvt_pk_bf16_f32 v137, v227, v228
	v_cvt_pk_bf16_f32 v138, v177, v192
	v_cvt_pk_bf16_f32 v139, v193, v194
	v_cvt_pk_bf16_f32 v132, v195, v221
; __device__ __forceinline__ u32x4 pack8(const float* f) { u32x4 w; w.x = cvt_pk_bf16(f[0], f[1]); w.y = cvt_pk_bf16(f[2], f[3]); w.z = cvt_pk_bf16(f[4], f[5]); w.w = cvt_pk_bf16(f[6], f[7]); return w; }
; __device__ __forceinline__ int v_st(int k, int c) { const int kk = (k & ~0xC) | ((k & 4) << 1) | ((k & 8) >> 1); return ((kk >> 3) * 4 + (c >> 5)) * 512 + ((kk & 7) * 32 + (c & 31)) * 2; }
; __device__ __forceinline__ int v_rd_base(int lane) { return ((lane & 3) << 3) | (((lane >> 2) & 3) << 6) | (((lane >> 4) & 1) << 5) | (((lane >> 5) & 1) << 8); }
; #define SLOAD(j) do { const int r0_ = TROW(j); const bf16_t* a_ = KVh + (size_t)(r0_ + sr) * LDKV + sc; const bf16_t* b_ = KVh + (size_t)(r0_ + 32 + sr) * LDKV + sc; \
;     vs0 = ld8(a_ + 128); vs1 = ld8(b_ + 128); ks0 = ld8(a_); ks1 = ld8(b_); kp0 = ld8(KPh + (size_t)(r0_ + pr) * LDKP + pc); } while (0)
; #define SWRITE(b) do { *(bf16x8*)(V_lds + (b) * SHM_V + vst0) = vs0; *(bf16x8*)(V_lds + (b) * SHM_V + vst1) = vs1; const int kc = sc * 2; \
;     *(bf16x8*)(KN_lds + (b) * SHM_KN + KSWZ(sr, kc)) = ks0; *(bf16x8*)(KN_lds + (b) * SHM_KN + KSWZ(32 + sr, kc)) = ks1; \
;     *(bf16x8*)(KP_lds + (b) * SHM_KP + KPSWZ(pr, pc * 2)) = kp0; } while (0)
; #define SWAIT() asm volatile("s_waitcnt vmcnt(0)" ::: "memory")
; __device__ __forceinline__ void attn_unit(const bf16_t* __restrict__ Qb, const bf16_t* __restrict__ KV, const bf16_t* __restrict__ KP, bf16_t* __restrict__ Ob, ...
;     ...
;     for (int d0 = 0; d0 < 12; ++d0) { const u32x4 w = pack8(qf[d0]); qr[d0] = *reinterpret_cast<const bf16x8*>(&w); }
;   }
;   const int sr = tid >> 4, sc = (tid & 15) * 8, vst0 = v_st(sr, sc), vst1 = v_st(32 + sr, sc);
;   const int pr = tid >> 3, pc = (tid & 7) * 8;
;   const int vb0 = (int)(uintptr_t)V_lds + v_rd_base(lane);
;   bf16x8 vs0, vs1, ks0, ks1, kp0;
;   const bf16_t* KVh = KV + h * 256; const bf16_t* KPh = KP + h * QKR;
;     ...
;   f32x16 pA0, pA1, pB0, pB1; float mnA, mnB, alA, alB; bf16x8 pa0, pa1, pa2, pa3;
;   SLOAD(0); SWAIT(); SWRITE(0); __syncthreads();
	v_cvt_pk_bf16_f32 v133, v219, v220
	v_cvt_pk_bf16_f32 v134, v218, v217
	v_cvt_pk_bf16_f32 v135, v90, v91
	v_cvt_pk_bf16_f32 v128, v84, v85
	v_cvt_pk_bf16_f32 v129, v86, v87
	v_cvt_pk_bf16_f32 v130, v80, v81
	v_cvt_pk_bf16_f32 v131, v82, v83
	v_cvt_pk_bf16_f32 v124, v76, v77
	v_cvt_pk_bf16_f32 v125, v78, v79
	v_cvt_pk_bf16_f32 v126, v72, v73
	v_cvt_pk_bf16_f32 v127, v74, v75
	v_cvt_pk_bf16_f32 v120, v68, v69
	v_cvt_pk_bf16_f32 v121, v70, v71
	v_cvt_pk_bf16_f32 v122, v64, v65
	v_cvt_pk_bf16_f32 v123, v66, v67
	v_cvt_pk_bf16_f32 v140, v56, v57
	v_cvt_pk_bf16_f32 v141, v58, v59
	v_cvt_pk_bf16_f32 v142, v169, v168
	v_cvt_pk_bf16_f32 v143, v167, v166
	v_cvt_pk_bf16_f32 v116, v165, v164
	v_cvt_pk_bf16_f32 v117, v163, v170
	v_cvt_pk_bf16_f32 v118, v171, v179
	v_cvt_pk_bf16_f32 v119, v180, v181
	v_cvt_pk_bf16_f32 v112, v60, v61
	v_cvt_pk_bf16_f32 v113, v62, v63
	v_cvt_pk_bf16_f32 v114, v182, v183
	v_cvt_pk_bf16_f32 v115, v54, v55
	v_cvt_pk_bf16_f32 v108, v52, v88
	v_lshlrev_b32_e32 v52, 3, v162
	v_sub_f32_e32 v24, v25, v24
	v_cvt_pk_bf16_f32 v109, v35, v37
	v_cvt_pk_bf16_f32 v110, v39, v32
	v_cvt_pk_bf16_f32 v111, v29, v26
	v_cvt_pk_bf16_f32 v104, v53, v34
	v_cvt_pk_bf16_f32 v105, v36, v38
	v_cvt_pk_bf16_f32 v106, v40, v28
	v_cvt_pk_bf16_f32 v107, v33, v27
	v_cvt_pk_bf16_f32 v100, v30, v24
	v_cvt_pk_bf16_f32 v101, v13, v10
	v_cvt_pk_bf16_f32 v102, v14, v8
	v_cvt_pk_bf16_f32 v103, v5, v2
	v_cvt_pk_bf16_f32 v96, v31, v12
	v_cvt_pk_bf16_f32 v97, v20, v11
	v_cvt_pk_bf16_f32 v98, v15, v4
	v_cvt_pk_bf16_f32 v99, v9, v0
	v_ashrrev_i32_e32 v198, 4, v162
	v_and_b32_e32 v0, 0x78, v52
	v_lshlrev_b32_e32 v48, 1, v0
	s_lshl_b32 s6, s3, 9
	v_add_u32_e32 v0, s31, v198
	s_add_u32 s6, s27, s6
	v_ashrrev_i32_e32 v1, 31, v0
	s_addc_u32 s7, s28, 0
	v_lshlrev_b64 v[0:1], 12, v[0:1]
	v_lshl_add_u64 v[0:1], s[6:7], 0, v[0:1]
	v_mov_b32_e32 v49, v173
	v_add_u32_e32 v53, s25, v198
	v_lshl_add_u64 v[8:9], v[0:1], 0, v[48:49]
	v_add_u32_e32 v0, 0x4020, v53
	v_ashrrev_i32_e32 v1, 31, v0
	v_lshlrev_b64 v[0:1], 12, v[0:1]
	v_lshl_add_u64 v[4:5], s[6:7], 0, v[0:1]
	global_load_dwordx4 v[0:3], v[8:9], off offset:256
	v_ashrrev_i32_e32 v199, 3, v162
	s_lshl_b32 s8, s3, 7
	v_add_u32_e32 v16, s31, v199
	s_add_u32 s8, s29, s8
	v_ashrrev_i32_e32 v17, 31, v16
	v_lshlrev_b32_e32 v72, 4, v162
	s_addc_u32 s9, s30, 0
	v_lshlrev_b64 v[16:17], 10, v[16:17]
	v_lshl_add_u64 v[12:13], v[4:5], 0, v[48:49]
	v_lshl_add_u64 v[16:17], s[8:9], 0, v[16:17]
	v_and_b32_e32 v50, 0x70, v72
	v_mov_b32_e32 v51, v173
	global_load_dwordx4 v[4:7], v[12:13], off offset:256
	v_lshl_add_u64 v[16:17], v[16:17], 0, v[50:51]
	global_load_dwordx4 v[8:11], v[8:9], off
	v_and_b32_e32 v20, 0xfffff0, v198
	global_load_dwordx4 v[12:15], v[12:13], off
	v_lshlrev_b32_e32 v21, 1, v198
	global_load_dwordx4 v[16:19], v[16:17], off
	v_and_or_b32 v20, v21, 8, v20
	v_lshrrev_b32_e32 v21, 1, v198
	v_lshrrev_b32_e32 v20, 1, v20
	v_bfe_u32 v22, v52, 5, 2
	v_and_b32_e32 v23, 3, v198
	v_or_b32_e32 v20, v20, v22
	v_and_or_b32 v21, v21, 4, v23
	v_lshlrev_b32_e32 v20, 9, v20
	v_lshlrev_b32_e32 v21, 6, v21
	v_and_b32_e32 v23, 48, v48
	v_or3_b32 v20, v20, v21, v23
	v_add_u32_e32 v200, 32, v198
	v_and_b32_e32 v24, 0xfffff0, v200
	v_lshlrev_b32_e32 v25, 1, v200
	v_add_u32_e32 v201, 0, v20
	v_and_or_b32 v24, v25, 8, v24
	s_waitcnt vmcnt(0)
	v_lshrrev_b32_e32 v24, 1, v24
	v_or_b32_e32 v22, v24, v22
	v_lshlrev_b32_e32 v22, 9, v22
	v_or3_b32 v21, v22, v21, v23
	v_add_u32_e32 v202, 0, v21
	s_add_i32 s31, 0, 0x10000
	v_and_b32_e32 v74, 63, v162
	v_mov_b32_e32 v77, 0xf149f2ca
	v_lshl_add_u64 v[180:181], s[6:7], 0, v[48:49]
	v_lshl_add_u64 v[182:183], s[8:9], 0, v[50:51]
	v_mov_b32_e32 v187, 0
	s_waitcnt vmcnt(4)
	ds_write_b128 v201, v[0:3]
	v_lshlrev_b32_e32 v0, 8, v198
	v_and_b32_e32 v1, 0xf0, v162
	v_bitop3_b32 v0, v48, v0, v1 bitop3:0xde
	v_add_u32_e32 v203, 0, v0
	v_lshlrev_b32_e32 v0, 8, v200
	v_bitop3_b32 v0, v48, v0, v1 bitop3:0xde
	v_add_u32_e32 v204, 0, v0
	v_lshlrev_b32_e32 v0, 7, v199
	v_and_b32_e32 v1, 0x70, v162
	v_bitop3_b32 v73, v50, v0, v1 bitop3:0xde
	v_add_u32_e32 v0, s31, v73
	v_add_u32_e32 v222, 0, v73
	s_waitcnt vmcnt(3)
	ds_write_b128 v202, v[4:7]
	v_add_u32_e32 v223, 0x12000, v222
	s_waitcnt vmcnt(2)
	v_lshrrev_b32_e32 v206, 4, v188
	v_and_b32_e32 v207, 0x13, v206
	v_and_b32_e32 v208, 4, v206
	v_lshl_or_b32 v207, v208, 1, v207
	v_and_b32_e32 v208, 8, v206
	v_lshrrev_b32_e32 v208, 1, v208
	v_or_b32_e32 v207, v207, v208
	v_and_b32_e32 v208, 15, v207
	v_and_b32_e32 v209, 15, v188
	v_xor_b32_e32 v208, v208, v209
	v_lshlrev_b32_e32 v208, 4, v208
	v_lshl_or_b32 v203, v207, 8, v208
	v_add_u32_e32 v204, 0x2000, v203
	v_lshrrev_b32_e32 v206, 3, v188
	v_and_b32_e32 v207, 0x33, v206
	v_and_b32_e32 v208, 4, v206
	v_lshl_or_b32 v207, v208, 1, v207
	v_and_b32_e32 v208, 8, v206
	v_lshrrev_b32_e32 v208, 1, v208
	v_or_b32_e32 v207, v207, v208
	v_bfe_u32 v208, v207, 1, 3
	v_and_b32_e32 v209, 7, v188
	v_xor_b32_e32 v208, v208, v209
	v_lshlrev_b32_e32 v208, 4, v208
	v_lshl_or_b32 v222, v207, 7, v208
	v_add_u32_e32 v0, s31, v222
	ds_write_b128 v203, v[8:11] offset:32768
	v_lshlrev_b32_e32 v8, 8, v184
	v_and_b32_e32 v9, 0xf0, v72
	s_waitcnt vmcnt(1)
	ds_write_b128 v204, v[12:15] offset:32768
	s_waitcnt vmcnt(0)
	ds_write_b128 v0, v[16:19]
	v_bitop3_b32 v0, v172, v8, v9 bitop3:0xde
	v_add_u32_e32 v205, 0, v0
	s_waitcnt lgkmcnt(0)
	s_barrier
; __device__ __forceinline__ int v_st(int k, int c) { const int kk = (k & ~0xC) | ((k & 4) << 1) | ((k & 8) >> 1); return ((kk >> 3) * 4 + (c >> 5)) * 512 + ((kk & 7) * 32 + (c & 31)) * 2; }
; __device__ __forceinline__ int v_rd_base(int lane) { return ((lane & 3) << 3) | (((lane >> 2) & 3) << 6) | (((lane >> 4) & 1) << 5) | (((lane >> 5) & 1) << 8); }
; #define SLOAD(j) do { const int r0_ = TROW(j); const bf16_t* a_ = KVh + (size_t)(r0_ + sr) * LDKV + sc; const bf16_t* b_ = KVh + (size_t)(r0_ + 32 + sr) * LDKV + sc; \
;     vs0 = ld8(a_ + 128); vs1 = ld8(b_ + 128); ks0 = ld8(a_); ks1 = ld8(b_); kp0 = ld8(KPh + (size_t)(r0_ + pr) * LDKP + pc); } while (0)
; #define SWRITE(b) do { *(bf16x8*)(V_lds + (b) * SHM_V + vst0) = vs0; *(bf16x8*)(V_lds + (b) * SHM_V + vst1) = vs1; const int kc = sc * 2; \
;     *(bf16x8*)(KN_lds + (b) * SHM_KN + KSWZ(sr, kc)) = ks0; *(bf16x8*)(KN_lds + (b) * SHM_KN + KSWZ(32 + sr, kc)) = ks1; \
;     *(bf16x8*)(KP_lds + (b) * SHM_KP + KPSWZ(pr, pc * 2)) = kp0; } while (0)
; #define SWAIT() asm volatile("s_waitcnt vmcnt(0)" ::: "memory")
; __device__ __forceinline__ void attn_unit(const bf16_t* __restrict__ Qb, const bf16_t* __restrict__ KV, const bf16_t* __restrict__ KP, bf16_t* __restrict__ Ob, ...
;     ...
;   const int sr = tid >> 4, sc = (tid & 15) * 8, vst0 = v_st(sr, sc), vst1 = v_st(32 + sr, sc);
;   const int pr = tid >> 3, pc = (tid & 7) * 8;
;   const int vb0 = (int)(uintptr_t)V_lds + v_rd_base(lane);
;   bf16x8 vs0, vs1, ks0, ks1, kp0;
;   const bf16_t* KVh = KV + h * 256; const bf16_t* KPh = KP + h * QKR;
;     ...
;   f32x16 pA0, pA1, pB0, pB1; float mnA, mnB, alA, alB; bf16x8 pa0, pa1, pa2, pa3;
;   SLOAD(0); SWAIT(); SWRITE(0); __syncthreads();
	s_movk_i32 s49, 0x1000
	s_waitcnt vmcnt(0)
	v_readfirstlane_b32 s40, v188
	s_nop 1
	s_lshr_b32 s40, s40, 6
	s_lshr_b32 s41, s40, 2
	v_and_b32_e32 v187, 0x3fffffc0, v188
	v_lshlrev_b32_e32 v179, 2, v187
	v_add_u32_e32 v179, 0x14000, v179
	v_lshl_add_u32 v186, v184, 2, v179
	v_and_b32_e32 v187, 63, v188
	v_cmp_gt_u32_e64 s[6:7], 32, v187
	s_add_i32 s31, s25, 0x4000
	s_lshl_b32 s44, s3, 9
	s_add_u32 s47, s27, s44
	s_addc_u32 s63, s28, 0
	s_lshl_b32 s44, s3, 7
	s_add_u32 s60, s29, s44
	s_addc_u32 s61, s30, 0
	v_lshrrev_b32_e32 v180, 4, v188
	v_lshlrev_b32_e32 v180, 12, v180
	v_and_b32_e32 v181, 15, v188
	v_lshl_or_b32 v180, v181, 4, v180
	v_lshrrev_b32_e32 v181, 3, v188
	v_lshlrev_b32_e32 v181, 10, v181
	v_and_b32_e32 v182, 7, v188
	v_lshl_or_b32 v181, v182, 4, v181
	v_lshlrev_b32_e32 v250, 8, v184
	v_and_b32_e32 v251, 15, v184
	v_lshlrev_b32_e32 v251, 4, v251
	v_or_b32_e32 v249, 0, v172
	v_xor_b32_e32 v249, v249, v251
	v_or_b32_e32 v249, v249, v250
	v_add_u32_e32 v160, 0x8000, v249
	v_or_b32_e32 v249, 32, v172
	v_xor_b32_e32 v249, v249, v251
	v_or_b32_e32 v249, v249, v250
	v_add_u32_e32 v161, 0x8000, v249
	v_or_b32_e32 v249, 64, v172
	v_xor_b32_e32 v249, v249, v251
	v_or_b32_e32 v249, v249, v250
	v_add_u32_e32 v162, 0x8000, v249
	v_or_b32_e32 v249, 96, v172
	v_xor_b32_e32 v249, v249, v251
	v_or_b32_e32 v249, v249, v250
	v_add_u32_e32 v163, 0x8000, v249
	v_or_b32_e32 v249, 128, v172
	v_xor_b32_e32 v249, v249, v251
	v_or_b32_e32 v249, v249, v250
	v_add_u32_e32 v164, 0x8000, v249
	v_or_b32_e32 v249, 160, v172
	v_xor_b32_e32 v249, v249, v251
	v_or_b32_e32 v249, v249, v250
	v_add_u32_e32 v165, 0x8000, v249
	v_or_b32_e32 v249, 192, v172
	v_xor_b32_e32 v249, v249, v251
	v_or_b32_e32 v249, v249, v250
	v_add_u32_e32 v166, 0x8000, v249
	v_or_b32_e32 v249, 224, v172
	v_xor_b32_e32 v249, v249, v251
	v_or_b32_e32 v249, v249, v250
	v_add_u32_e32 v167, 0x8000, v249
	v_lshlrev_b32_e32 v250, 7, v184
	v_lshrrev_b32_e32 v251, 1, v184
	v_and_b32_e32 v251, 7, v251
	v_lshlrev_b32_e32 v251, 4, v251
	v_or_b32_e32 v249, 0, v172
	v_xor_b32_e32 v249, v249, v251
	v_or_b32_e32 v249, v249, v250
	v_add_u32_e32 v168, 0x10000, v249
	v_or_b32_e32 v249, 32, v172
	v_xor_b32_e32 v249, v249, v251
	v_or_b32_e32 v249, v249, v250
	v_add_u32_e32 v169, 0x10000, v249
	v_or_b32_e32 v249, 64, v172
	v_xor_b32_e32 v249, v249, v251
	v_or_b32_e32 v249, v249, v250
	v_add_u32_e32 v170, 0x10000, v249
	v_or_b32_e32 v249, 96, v172
	v_xor_b32_e32 v249, v249, v251
	v_or_b32_e32 v249, v249, v250
	v_add_u32_e32 v171, 0x10000, v249
	v_and_b32_e32 v187, 63, v188
	v_lshlrev_b32_e32 v249, 3, v187
	v_lshlrev_b32_e32 v250, 4, v187
	v_and_b32_e32 v250, 0xc0, v250
	v_and_or_b32 v250, v249, 24, v250
	v_lshlrev_b32_e32 v251, 1, v187
	v_and_b32_e32 v251, 32, v251
	v_and_b32_e32 v249, 0x100, v249
	v_or3_b32 v174, v250, v251, v249
	v_mov_b32_e32 v244, v201
	v_add_u32_e32 v245, 0x4000, v201
	v_add_u32_e32 v246, 0xc000, v203
	v_add_u32_e32 v248, 0x12000, v222
	v_mov_b32_e32 v175, 0
	s_mov_b32 s62, 0
	s_mov_b32 s64, 0x42800000
	v_mov_b32_e32 v176, 0
	v_mov_b32_e32 v0, 0
	v_mov_b32_e32 v1, 0
	v_mov_b32_e32 v2, 0
	v_mov_b32_e32 v3, 0
	v_mov_b32_e32 v4, 0
	v_mov_b32_e32 v5, 0
	v_mov_b32_e32 v6, 0
	v_mov_b32_e32 v7, 0
	v_mov_b32_e32 v8, 0
	v_mov_b32_e32 v9, 0
	v_mov_b32_e32 v10, 0
	v_mov_b32_e32 v11, 0
	v_mov_b32_e32 v12, 0
	v_mov_b32_e32 v13, 0
	v_mov_b32_e32 v14, 0
	v_mov_b32_e32 v15, 0
	v_mov_b32_e32 v16, 0
	v_mov_b32_e32 v17, 0
	v_mov_b32_e32 v18, 0
	v_mov_b32_e32 v19, 0
	v_mov_b32_e32 v20, 0
	v_mov_b32_e32 v21, 0
	v_mov_b32_e32 v22, 0
	v_mov_b32_e32 v23, 0
	v_mov_b32_e32 v24, 0
	v_mov_b32_e32 v25, 0
	v_mov_b32_e32 v26, 0
	v_mov_b32_e32 v27, 0
	v_mov_b32_e32 v28, 0
	v_mov_b32_e32 v29, 0
	v_mov_b32_e32 v30, 0
	v_mov_b32_e32 v31, 0
	v_mov_b32_e32 v32, 0
	v_mov_b32_e32 v33, 0
	v_mov_b32_e32 v34, 0
	v_mov_b32_e32 v35, 0
	v_mov_b32_e32 v36, 0
	v_mov_b32_e32 v37, 0
	v_mov_b32_e32 v38, 0
	v_mov_b32_e32 v39, 0
	v_mov_b32_e32 v40, 0
	v_mov_b32_e32 v41, 0
	v_mov_b32_e32 v42, 0
	v_mov_b32_e32 v43, 0
	v_mov_b32_e32 v44, 0
	v_mov_b32_e32 v45, 0
	v_mov_b32_e32 v46, 0
	v_mov_b32_e32 v47, 0
	v_mov_b32_e32 v48, 0
	v_mov_b32_e32 v49, 0
	v_mov_b32_e32 v50, 0
	v_mov_b32_e32 v51, 0
	v_mov_b32_e32 v52, 0
	v_mov_b32_e32 v53, 0
	v_mov_b32_e32 v54, 0
	v_mov_b32_e32 v55, 0
	v_mov_b32_e32 v56, 0
	v_mov_b32_e32 v57, 0
	v_mov_b32_e32 v58, 0
	v_mov_b32_e32 v59, 0
	v_mov_b32_e32 v60, 0
	v_mov_b32_e32 v61, 0
	v_mov_b32_e32 v62, 0
	v_mov_b32_e32 v63, 0
	v_mov_b32_e32 v144, 0
	v_mov_b32_e32 v145, 0
	v_mov_b32_e32 v146, 0
	v_mov_b32_e32 v147, 0
	v_mov_b32_e32 v148, 0
	v_mov_b32_e32 v149, 0
	v_mov_b32_e32 v150, 0
	v_mov_b32_e32 v151, 0
	v_mov_b32_e32 v152, 0
	v_mov_b32_e32 v153, 0
	v_mov_b32_e32 v154, 0
	v_mov_b32_e32 v155, 0
	v_mov_b32_e32 v156, 0
	v_mov_b32_e32 v157, 0
	v_mov_b32_e32 v158, 0
	v_mov_b32_e32 v159, 0
	s_mov_b32 s35, 0
	s_mov_b32 s11, 0
	s_mov_b32 s65, 0
	s_mov_b32 s72, 1
	s_add_i32 s36, s31, 64
	s_mov_b32 s37, s31
	s_lshl_b32 s44, s36, 12
	s_add_u32 s50, s47, s44
	s_addc_u32 s51, s63, 0
	s_add_u32 s52, s50, 0x20000
	s_addc_u32 s53, s51, 0
	s_lshl_b32 s44, s37, 12
	s_add_u32 s54, s47, s44
	s_addc_u32 s55, s63, 0
	s_add_u32 s56, s54, 0x20000
	s_addc_u32 s57, s55, 0
	s_lshl_b32 s44, s36, 10
	s_add_u32 s58, s60, s44
	s_addc_u32 s59, s61, 0
	global_load_dwordx4 v[208:211], v180, s[50:51]
	global_load_dwordx4 v[212:215], v180, s[52:53]
	global_load_dwordx4 v[216:219], v181, s[58:59]
	s_add_i32 s36, s31, 128
	s_lshl_b32 s44, s36, 12
	s_add_u32 s50, s47, s44
	s_addc_u32 s51, s63, 0
	s_add_u32 s52, s50, 0x20000
	s_addc_u32 s53, s51, 0
	s_lshl_b32 s44, s37, 12
	s_add_u32 s54, s47, s44
	s_addc_u32 s55, s63, 0
	s_add_u32 s56, s54, 0x20000
	s_addc_u32 s57, s55, 0
	s_lshl_b32 s44, s36, 10
	s_add_u32 s58, s60, s44
	s_addc_u32 s59, s61, 0
	global_load_dwordx4 v[232:235], v180, s[50:51]
	global_load_dwordx4 v[236:239], v180, s[52:53]
	global_load_dwordx4 v[224:227], v180, s[54:55] offset:256
	global_load_dwordx4 v[228:231], v180, s[56:57] offset:256
	global_load_dwordx4 v[240:243], v181, s[58:59]
	s_movk_i32 s75, 0x4000
	s_movk_i32 s98, 0x2000
	s_cmp_eq_u32 s72, 0
	s_cselect_b32 s75, s75, 0xc000
	s_cselect_b32 s98, s98, 0xa000
	s_cmp_eq_u32 s72, 2
	s_cselect_b32 s75, 0xffff0000, s75
	s_cselect_b32 s98, 0xffff4000, s98
	s_cselect_b32 s72, -1, s72
	s_add_i32 s72, s72, 1
	s_waitcnt vmcnt(5)
	ds_write_b128 v246, v[208:211]
	ds_write_b128 v246, v[212:215] offset:8192
	ds_write_b128 v248, v[216:219]
	v_add_u32_e32 v246, s75, v246
	v_add_u32_e32 v248, s98, v248
	s_waitcnt lgkmcnt(0)
	s_barrier
; #define SBAR() __builtin_amdgcn_sched_barrier(0)
; #define SLOAD(j) do { const int r0_ = TROW(j); const bf16_t* a_ = KVh + (size_t)(r0_ + sr) * LDKV + sc; const bf16_t* b_ = KVh + (size_t)(r0_ + 32 + sr) * LDKV + sc; \
;     vs0 = ld8(a_ + 128); vs1 = ld8(b_ + 128); ks0 = ld8(a_); ks1 = ld8(b_); kp0 = ld8(KPh + (size_t)(r0_ + pr) * LDKP + pc); } while (0)
; #define SWRITE(b) do { *(bf16x8*)(V_lds + (b) * SHM_V + vst0) = vs0; *(bf16x8*)(V_lds + (b) * SHM_V + vst1) = vs1; const int kc = sc * 2; \
;     *(bf16x8*)(KN_lds + (b) * SHM_KN + KSWZ(sr, kc)) = ks0; *(bf16x8*)(KN_lds + (b) * SHM_KN + KSWZ(32 + sr, kc)) = ks1; \
;     *(bf16x8*)(KP_lds + (b) * SHM_KP + KPSWZ(pr, pc * 2)) = kp0; } while (0)
; #define SWAIT() asm volatile("s_waitcnt vmcnt(0)" ::: "memory")
; __device__ __forceinline__ void qkt(f32x16& p0, f32x16& p1, const char* Kn, const char* Kp, const bf16x8* qr, int r32, int hi) {
;   p0 = f32x16{}; p1 = f32x16{};
; #pragma unroll
;   for (int d0 = 0; d0 < 8; ++d0) { int cb = (d0 * 16 + hi * 8) * 2;
;     bf16x8 b0 = *reinterpret_cast<const bf16x8*>(Kn + KSWZ(r32, cb));
;     bf16x8 b1 = *reinterpret_cast<const bf16x8*>(Kn + KSWZ(32 + r32, cb));
;     p0 = __builtin_amdgcn_mfma_f32_32x32x16_bf16(b0, qr[d0], p0, 0, 0, 0);
;     p1 = __builtin_amdgcn_mfma_f32_32x32x16_bf16(b1, qr[d0], p1, 0, 0, 0); }
; #pragma unroll
;   for (int d1 = 0; d1 < 4; ++d1) { int cb = (d1 * 16 + hi * 8) * 2;
;     bf16x8 b0 = *reinterpret_cast<const bf16x8*>(Kp + KPSWZ(r32, cb));
;     bf16x8 b1 = *reinterpret_cast<const bf16x8*>(Kp + KPSWZ(32 + r32, cb));
;     p0 = __builtin_amdgcn_mfma_f32_32x32x16_bf16(b0, qr[8 + d1], p0, 0, 0, 0);
;     p1 = __builtin_amdgcn_mfma_f32_32x32x16_bf16(b1, qr[8 + d1], p1, 0, 0, 0); }
; __device__ __forceinline__ void attn_unit(const bf16_t* __restrict__ Qb, const bf16_t* __restrict__ KV, const bf16_t* __restrict__ KP, bf16_t* __restrict__ Ob, ...
;     ...
;   for (int j = 1; j + 1 < NT; j += 2) {
;     SBAR(); qkt(pB0, pB1, KN_lds + SHM_KN, KP_lds + SHM_KP, qr, r32, hi);
;     finishSM(pA0, pA1, alA, l_reg, pa0, pa1, pa2, pa3); SBAR();
;     SLOAD(j + 1); SBAR();
;     pv_d0(o, vb0, pa0, pa1, pa2, pa3); partialSM(pB0, pB1, m_reg, mnB, alB);
;     __syncthreads(); SWAIT(); SWRITE(0);
;     RESC(alB); __syncthreads();
	s_cmp_eq_u32 s41, 0
	s_cbranch_scc1 .Lpp_ga
	s_add_i32 s36, s35, 3
	s_min_u32 s36, s36, 67
	s_lshl_b32 s44, s36, 6
	s_add_i32 s45, s31, s44
	s_add_i32 s46, s24, s44
	s_add_i32 s46, s46, 0xffffff00
	s_cmp_lt_u32 s36, 4
	s_cselect_b32 s36, s45, s46
	s_add_i32 s37, s35, 1
	s_min_u32 s37, s37, 67
	s_lshl_b32 s44, s37, 6
	s_add_i32 s45, s31, s44
	s_add_i32 s46, s24, s44
	s_add_i32 s46, s46, 0xffffff00
	s_cmp_lt_u32 s37, 4
	s_cselect_b32 s37, s45, s46
	s_add_i32 s35, s35, 1
	s_lshl_b32 s44, s36, 12
	s_add_u32 s50, s47, s44
	s_addc_u32 s51, s63, 0
	s_add_u32 s52, s50, 0x20000
	s_addc_u32 s53, s51, 0
	s_lshl_b32 s44, s37, 12
	s_add_u32 s54, s47, s44
	s_addc_u32 s55, s63, 0
	s_add_u32 s56, s54, 0x20000
	s_addc_u32 s57, s55, 0
	s_lshl_b32 s44, s36, 10
	s_add_u32 s58, s60, s44
	s_addc_u32 s59, s61, 0
	s_movk_i32 s73, 0x4000
	s_movk_i32 s74, 0x2000
	s_cmp_eq_u32 s65, 0
	s_cselect_b32 s73, s73, 0xc000
	s_cselect_b32 s74, s74, 0xa000
	s_cmp_eq_u32 s65, 2
	s_cselect_b32 s73, 0xffff0000, s73
	s_cselect_b32 s74, 0xffff4000, s74
	s_cselect_b32 s65, -1, s65
	s_add_i32 s65, s65, 1
	s_movk_i32 s75, 0x4000
	s_movk_i32 s98, 0x2000
	s_cmp_eq_u32 s72, 0
	s_cselect_b32 s75, s75, 0xc000
	s_cselect_b32 s98, s98, 0xa000
	s_cmp_eq_u32 s72, 2
	s_cselect_b32 s75, 0xffff0000, s75
	s_cselect_b32 s98, 0xffff4000, s98
	s_cselect_b32 s72, -1, s72
	s_add_i32 s72, s72, 1
	s_waitcnt vmcnt(0)
	ds_write_b128 v246, v[232:235]
	ds_write_b128 v246, v[236:239] offset:8192
	ds_write_b128 v248, v[240:243]
	ds_write_b128 v244, v[224:227]
	ds_write_b128 v244, v[228:231] offset:8192
	v_add_u32_e32 v246, s75, v246
	v_add_u32_e32 v248, s98, v248
	global_load_dwordx4 v[232:235], v180, s[50:51]
	global_load_dwordx4 v[236:239], v180, s[52:53]
	global_load_dwordx4 v[224:227], v180, s[54:55] offset:256
	global_load_dwordx4 v[228:231], v180, s[56:57] offset:256
	global_load_dwordx4 v[240:243], v181, s[58:59]
	v_swap_b32 v244, v245
	s_sub_i32 s65, s65, 1
	ds_read_b128 v[192:195], v160
	ds_read_b128 v[196:199], v160 offset:8192
	ds_read_b128 v[200:203], v161
	ds_read_b128 v[204:207], v161 offset:8192
	ds_read_b128 v[208:211], v162
	ds_read_b128 v[212:215], v162 offset:8192
	ds_read_b128 v[216:219], v163
	ds_read_b128 v[220:223], v163 offset:8192
	s_waitcnt lgkmcnt(6)
	v_mfma_f32_32x32x16_bf16 v[80:95], v[192:195], v[136:139], 0
	v_mfma_f32_32x32x16_bf16 v[64:79], v[196:199], v[136:139], 0
	s_add_i32 s36, s35, 3
	s_min_u32 s36, s36, 67
	s_lshl_b32 s44, s36, 6
	s_add_i32 s45, s31, s44
	s_add_i32 s46, s24, s44
	ds_read_b128 v[192:195], v164
	ds_read_b128 v[196:199], v164 offset:8192
	s_waitcnt lgkmcnt(6)
	v_mfma_f32_32x32x16_bf16 v[80:95], v[200:203], v[132:135], v[80:95]
	v_mfma_f32_32x32x16_bf16 v[64:79], v[204:207], v[132:135], v[64:79]
	s_add_i32 s46, s46, 0xffffff00
	s_cmp_lt_u32 s36, 4
	s_cselect_b32 s36, s45, s46
	s_add_i32 s37, s35, 1
	s_min_u32 s37, s37, 67
	ds_read_b128 v[200:203], v165
	ds_read_b128 v[204:207], v165 offset:8192
	s_waitcnt lgkmcnt(6)
	v_mfma_f32_32x32x16_bf16 v[80:95], v[208:211], v[128:131], v[80:95]
	v_mfma_f32_32x32x16_bf16 v[64:79], v[212:215], v[128:131], v[64:79]
	s_lshl_b32 s44, s37, 6
	s_add_i32 s45, s31, s44
	s_add_i32 s46, s24, s44
	s_add_i32 s46, s46, 0xffffff00
	s_cmp_lt_u32 s37, 4
	ds_read_b128 v[208:211], v166
	ds_read_b128 v[212:215], v166 offset:8192
	s_waitcnt lgkmcnt(6)
	v_mfma_f32_32x32x16_bf16 v[80:95], v[216:219], v[124:127], v[80:95]
	v_mfma_f32_32x32x16_bf16 v[64:79], v[220:223], v[124:127], v[64:79]
	s_cselect_b32 s37, s45, s46
	s_add_i32 s35, s35, 1
	s_lshl_b32 s44, s36, 12
	s_add_u32 s50, s47, s44
	s_addc_u32 s51, s63, 0
	ds_read_b128 v[216:219], v167
	ds_read_b128 v[220:223], v167 offset:8192
	s_waitcnt lgkmcnt(6)
	v_mfma_f32_32x32x16_bf16 v[80:95], v[192:195], v[120:123], v[80:95]
	v_mfma_f32_32x32x16_bf16 v[64:79], v[196:199], v[120:123], v[64:79]
	s_add_u32 s52, s50, 0x20000
	s_addc_u32 s53, s51, 0
	s_lshl_b32 s44, s37, 12
	s_add_u32 s54, s47, s44
	s_addc_u32 s55, s63, 0
	ds_read_b128 v[192:195], v168
	ds_read_b128 v[196:199], v168 offset:4096
	s_waitcnt lgkmcnt(6)
	v_mfma_f32_32x32x16_bf16 v[80:95], v[200:203], v[140:143], v[80:95]
	v_mfma_f32_32x32x16_bf16 v[64:79], v[204:207], v[140:143], v[64:79]
	s_add_u32 s56, s54, 0x20000
	s_addc_u32 s57, s55, 0
	s_lshl_b32 s44, s36, 10
	s_add_u32 s58, s60, s44
	s_addc_u32 s59, s61, 0
	ds_read_b128 v[200:203], v169
	ds_read_b128 v[204:207], v169 offset:4096
	s_waitcnt lgkmcnt(6)
	v_mfma_f32_32x32x16_bf16 v[80:95], v[208:211], v[116:119], v[80:95]
	v_mfma_f32_32x32x16_bf16 v[64:79], v[212:215], v[116:119], v[64:79]
	s_movk_i32 s73, 0x4000
	s_movk_i32 s74, 0x2000
	s_cmp_eq_u32 s65, 0
	s_cselect_b32 s73, s73, 0xc000
	s_cselect_b32 s74, s74, 0xa000
	ds_read_b128 v[208:211], v170
	ds_read_b128 v[212:215], v170 offset:4096
	s_waitcnt lgkmcnt(6)
	v_mfma_f32_32x32x16_bf16 v[80:95], v[216:219], v[112:115], v[80:95]
	v_mfma_f32_32x32x16_bf16 v[64:79], v[220:223], v[112:115], v[64:79]
	s_cmp_eq_u32 s65, 2
	s_cselect_b32 s73, 0xffff0000, s73
	s_cselect_b32 s74, 0xffff4000, s74
	s_cselect_b32 s65, -1, s65
	s_add_i32 s65, s65, 1
	ds_read_b128 v[216:219], v171
	ds_read_b128 v[220:223], v171 offset:4096
	s_waitcnt lgkmcnt(6)
	v_mfma_f32_32x32x16_bf16 v[80:95], v[192:195], v[108:111], v[80:95]
	v_mfma_f32_32x32x16_bf16 v[64:79], v[196:199], v[108:111], v[64:79]
	s_movk_i32 s75, 0x4000
	s_movk_i32 s98, 0x2000
	s_cmp_eq_u32 s72, 0
	s_cselect_b32 s75, s75, 0xc000
	s_cselect_b32 s98, s98, 0xa000
	s_waitcnt lgkmcnt(4)
	v_mfma_f32_32x32x16_bf16 v[80:95], v[200:203], v[104:107], v[80:95]
	v_mfma_f32_32x32x16_bf16 v[64:79], v[204:207], v[104:107], v[64:79]
	s_cmp_eq_u32 s72, 2
	s_cselect_b32 s75, 0xffff0000, s75
	s_cselect_b32 s98, 0xffff4000, s98
	s_cselect_b32 s72, -1, s72
	s_add_i32 s72, s72, 1
	s_waitcnt lgkmcnt(2)
	v_mfma_f32_32x32x16_bf16 v[80:95], v[208:211], v[100:103], v[80:95]
	v_mfma_f32_32x32x16_bf16 v[64:79], v[212:215], v[100:103], v[64:79]
	s_waitcnt lgkmcnt(0)
	v_mfma_f32_32x32x16_bf16 v[80:95], v[216:219], v[96:99], v[80:95]
	v_mfma_f32_32x32x16_bf16 v[64:79], v[220:223], v[96:99], v[64:79]
	s_nop 7
	s_nop 7
	s_nop 7
; #define SBAR() __builtin_amdgcn_sched_barrier(0)
; #define SLOAD(j) do { const int r0_ = TROW(j); const bf16_t* a_ = KVh + (size_t)(r0_ + sr) * LDKV + sc; const bf16_t* b_ = KVh + (size_t)(r0_ + 32 + sr) * LDKV + sc; \
;     vs0 = ld8(a_ + 128); vs1 = ld8(b_ + 128); ks0 = ld8(a_); ks1 = ld8(b_); kp0 = ld8(KPh + (size_t)(r0_ + pr) * LDKP + pc); } while (0)
; __device__ __forceinline__ void partialSM(f32x16& p0, f32x16& p1, float& m_reg, float& mn, float& alpha) {
;   constexpr float C = SCALE * 1.4426950408889634f;
;   float pmax = p0[0]; for (int r = 1; r < 16; ++r) pmax = fmaxf(pmax, p0[r]); for (int r = 0; r < 16; ++r) pmax = fmaxf(pmax, p1[r]);
;   { auto rr = __builtin_amdgcn_permlane32_swap(__float_as_uint(pmax), __float_as_uint(pmax), false, false);
;     pmax = fmaxf(__uint_as_float(rr[0]), __uint_as_float(rr[1])); }
;   if (__builtin_expect(__all(pmax - m_reg <= THR / SCALE), 1)) { mn = m_reg; alpha = 1.f; }
;   else { mn = fmaxf(m_reg, pmax); alpha = __builtin_amdgcn_exp2f((m_reg - mn) * C); m_reg = mn; }
;   float mnC = -mn * C;
;   for (int r = 0; r < 16; ++r) p0[r] = fmaf(p0[r], C, mnC); for (int r = 0; r < 16; ++r) p1[r] = fmaf(p1[r], C, mnC);
;   for (int r = 0; r < 16; ++r) p0[r] = __builtin_amdgcn_exp2f(p0[r]);
; }
; __device__ __forceinline__ void finishSM(f32x16& p0, f32x16& p1, float alpha, float& l_reg, bf16x8& pa0, bf16x8& pa1, bf16x8& pa2, bf16x8& pa3) {
;   for (int r = 0; r < 16; ++r) p1[r] = __builtin_amdgcn_exp2f(p1[r]);
;   float ps = 0; for (int r = 0; r < 16; ++r) ps += p0[r]; for (int r = 0; r < 16; ++r) ps += p1[r];
;   { auto rr = __builtin_amdgcn_permlane32_swap(__float_as_uint(ps), __float_as_uint(ps), false, false);
;     ps = __uint_as_float(rr[0]) + __uint_as_float(rr[1]); }
;   l_reg = l_reg * alpha + ps;
;     ...
;   PK4(p0, 0, pa0); PK4(p0, 8, pa1); PK4(p1, 0, pa2); PK4(p1, 8, pa3);
; __device__ __forceinline__ void attn_unit(const bf16_t* __restrict__ Qb, const bf16_t* __restrict__ KV, const bf16_t* __restrict__ KP, bf16_t* __restrict__ Ob, ...
;     ...
;   for (int j = 1; j + 1 < NT; j += 2) {
;     SBAR(); qkt(pB0, pB1, KN_lds + SHM_KN, KP_lds + SHM_KP, qr, r32, hi);
;     finishSM(pA0, pA1, alA, l_reg, pa0, pa1, pa2, pa3); SBAR();
;     SLOAD(j + 1); SBAR();
;     pv_d0(o, vb0, pa0, pa1, pa2, pa3); partialSM(pB0, pB1, m_reg, mnB, alB);
;     __syncthreads(); SWAIT(); SWRITE(0);
;     RESC(alB); __syncthreads();
.Lpp_loop:
	s_barrier
	v_add_u32_e32 v160, s73, v160
	v_add_u32_e32 v161, s73, v161
	v_add_u32_e32 v162, s73, v162
	v_add_u32_e32 v163, s73, v163
	v_add_u32_e32 v164, s73, v164
	v_add_u32_e32 v165, s73, v165
	v_add_u32_e32 v166, s73, v166
	v_add_u32_e32 v167, s73, v167
	v_add_u32_e32 v168, s74, v168
	v_add_u32_e32 v169, s74, v169
	v_add_u32_e32 v170, s74, v170
	v_add_u32_e32 v171, s74, v171
	ds_read_b128 v[192:195], v160
	ds_read_b128 v[196:199], v160 offset:8192
	ds_read_b128 v[200:203], v161
	ds_read_b128 v[204:207], v161 offset:8192
	ds_read_b128 v[208:211], v162
	ds_read_b128 v[212:215], v162 offset:8192
	ds_read_b128 v[216:219], v163
	ds_read_b128 v[220:223], v163 offset:8192
	v_max3_f32 v250, v80, v81, v82
	v_max3_f32 v250, v250, v83, v84
	v_max3_f32 v250, v250, v85, v86
	v_max3_f32 v250, v250, v87, v88
	v_max3_f32 v250, v250, v89, v90
	v_max3_f32 v250, v250, v91, v92
	v_max3_f32 v250, v250, v93, v94
	v_max3_f32 v250, v250, v95, v64
	v_max3_f32 v250, v250, v65, v66
	v_max3_f32 v250, v250, v67, v68
	v_max3_f32 v250, v250, v69, v70
	v_max3_f32 v250, v250, v71, v72
	v_max3_f32 v250, v250, v73, v74
	v_max3_f32 v250, v250, v75, v76
	v_max3_f32 v250, v250, v77, v78
	v_max3_f32 v250, v250, v79, v79
	v_cmp_lt_f32_e64 vcc, s64, |v250|
	s_waitcnt vmcnt(0)
	ds_write_b128 v246, v[232:235]
	ds_write_b128 v246, v[236:239] offset:8192
	ds_write_b128 v248, v[240:243]
	ds_write_b128 v244, v[224:227]
	ds_write_b128 v244, v[228:231] offset:8192
	v_add_u32_e32 v246, s75, v246
	v_add_u32_e32 v248, s98, v248
	global_load_dwordx4 v[232:235], v180, s[50:51]
	global_load_dwordx4 v[236:239], v180, s[52:53]
	global_load_dwordx4 v[224:227], v180, s[54:55] offset:256
	global_load_dwordx4 v[228:231], v180, s[56:57] offset:256
	global_load_dwordx4 v[240:243], v181, s[58:59]
	s_cmp_lg_u32 s62, 0
	s_cbranch_scc1 .Lpp_safe_Ba
	s_cbranch_vccnz .Lpp_sw_Ba
	v_exp_f32_e32 v80, v80
	v_exp_f32_e32 v81, v81
	v_exp_f32_e32 v82, v82
	v_exp_f32_e32 v83, v83
	v_exp_f32_e32 v84, v84
	v_exp_f32_e32 v85, v85
	v_exp_f32_e32 v86, v86
	v_exp_f32_e32 v87, v87
	v_exp_f32_e32 v88, v88
	v_exp_f32_e32 v89, v89
	v_exp_f32_e32 v90, v90
	v_exp_f32_e32 v91, v91
	v_exp_f32_e32 v92, v92
	v_exp_f32_e32 v93, v93
	v_exp_f32_e32 v94, v94
	v_exp_f32_e32 v95, v95
	v_exp_f32_e32 v64, v64
	v_exp_f32_e32 v65, v65
	v_exp_f32_e32 v66, v66
	v_exp_f32_e32 v67, v67
	v_exp_f32_e32 v68, v68
	v_exp_f32_e32 v69, v69
	v_exp_f32_e32 v70, v70
	v_exp_f32_e32 v71, v71
	v_exp_f32_e32 v72, v72
	v_exp_f32_e32 v73, v73
	v_exp_f32_e32 v74, v74
	v_exp_f32_e32 v75, v75
	v_exp_f32_e32 v76, v76
	v_exp_f32_e32 v77, v77
	v_exp_f32_e32 v78, v78
	v_exp_f32_e32 v79, v79
	v_add_f32_e32 v249, v80, v81
	v_add_f32_e32 v250, v82, v83
	v_add_f32_e32 v251, v84, v85
	v_add_f32_e32 v182, v86, v87
	v_add_f32_e32 v249, v88, v249
	v_add_f32_e32 v250, v89, v250
	v_add_f32_e32 v251, v90, v251
	v_add_f32_e32 v182, v91, v182
	v_add_f32_e32 v249, v92, v249
	v_add_f32_e32 v250, v93, v250
	v_add_f32_e32 v251, v94, v251
	v_add_f32_e32 v182, v95, v182
	v_add_f32_e32 v249, v64, v249
	v_add_f32_e32 v250, v65, v250
	v_add_f32_e32 v251, v66, v251
	v_add_f32_e32 v182, v67, v182
	v_add_f32_e32 v249, v68, v249
	v_add_f32_e32 v250, v69, v250
	v_add_f32_e32 v251, v70, v251
	v_add_f32_e32 v182, v71, v182
	v_add_f32_e32 v249, v72, v249
	v_add_f32_e32 v250, v73, v250
	v_add_f32_e32 v251, v74, v251
	v_add_f32_e32 v182, v75, v182
	v_add_f32_e32 v249, v76, v249
	v_add_f32_e32 v250, v77, v250
	v_add_f32_e32 v251, v78, v251
	v_add_f32_e32 v182, v79, v182
	v_add_f32_e32 v249, v249, v250
	v_add_f32_e32 v251, v251, v182
	v_add_f32_e32 v249, v249, v251
	v_add_f32_e32 v176, v176, v249
	v_cvt_pk_bf16_f32 v144, v80, v81
	v_cvt_pk_bf16_f32 v145, v82, v83
	v_cvt_pk_bf16_f32 v146, v84, v85
	v_cvt_pk_bf16_f32 v147, v86, v87
	v_cvt_pk_bf16_f32 v148, v88, v89
	v_cvt_pk_bf16_f32 v149, v90, v91
	v_cvt_pk_bf16_f32 v150, v92, v93
	v_cvt_pk_bf16_f32 v151, v94, v95
	v_cvt_pk_bf16_f32 v152, v64, v65
	v_cvt_pk_bf16_f32 v153, v66, v67
	v_cvt_pk_bf16_f32 v154, v68, v69
	v_cvt_pk_bf16_f32 v155, v70, v71
	v_cvt_pk_bf16_f32 v156, v72, v73
	v_cvt_pk_bf16_f32 v157, v74, v75
	v_cvt_pk_bf16_f32 v158, v76, v77
	v_cvt_pk_bf16_f32 v159, v78, v79
.Lpp_send_Ba:
	s_add_i32 s11, s11, 1
	s_waitcnt lgkmcnt(6)
	v_mfma_f32_32x32x16_bf16 v[80:95], v[192:195], v[136:139], 0
	v_mfma_f32_32x32x16_bf16 v[64:79], v[196:199], v[136:139], 0
	s_add_i32 s36, s35, 3
	s_min_u32 s36, s36, 67
	s_lshl_b32 s44, s36, 6
	s_add_i32 s45, s31, s44
	s_add_i32 s46, s24, s44
	ds_read_b128 v[192:195], v164
	ds_read_b128 v[196:199], v164 offset:8192
	s_waitcnt lgkmcnt(6)
	v_mfma_f32_32x32x16_bf16 v[80:95], v[200:203], v[132:135], v[80:95]
	v_mfma_f32_32x32x16_bf16 v[64:79], v[204:207], v[132:135], v[64:79]
	s_add_i32 s46, s46, 0xffffff00
	s_cmp_lt_u32 s36, 4
	s_cselect_b32 s36, s45, s46
	s_add_i32 s37, s35, 1
	s_min_u32 s37, s37, 67
	ds_read_b128 v[200:203], v165
	ds_read_b128 v[204:207], v165 offset:8192
	s_waitcnt lgkmcnt(6)
	v_mfma_f32_32x32x16_bf16 v[80:95], v[208:211], v[128:131], v[80:95]
	v_mfma_f32_32x32x16_bf16 v[64:79], v[212:215], v[128:131], v[64:79]
	s_lshl_b32 s44, s37, 6
	s_add_i32 s45, s31, s44
	s_add_i32 s46, s24, s44
	s_add_i32 s46, s46, 0xffffff00
	s_cmp_lt_u32 s37, 4
	ds_read_b128 v[208:211], v166
	ds_read_b128 v[212:215], v166 offset:8192
	s_waitcnt lgkmcnt(6)
	v_mfma_f32_32x32x16_bf16 v[80:95], v[216:219], v[124:127], v[80:95]
	v_mfma_f32_32x32x16_bf16 v[64:79], v[220:223], v[124:127], v[64:79]
	s_cselect_b32 s37, s45, s46
	s_add_i32 s35, s35, 1
	s_lshl_b32 s44, s36, 12
	s_add_u32 s50, s47, s44
	s_addc_u32 s51, s63, 0
	ds_read_b128 v[216:219], v167
	ds_read_b128 v[220:223], v167 offset:8192
	s_waitcnt lgkmcnt(6)
; #define SBAR() __builtin_amdgcn_sched_barrier(0)
; __device__ __forceinline__ void qkt(f32x16& p0, f32x16& p1, const char* Kn, const char* Kp, const bf16x8* qr, int r32, int hi) {
;   p0 = f32x16{}; p1 = f32x16{};
; #pragma unroll
;   for (int d0 = 0; d0 < 8; ++d0) { int cb = (d0 * 16 + hi * 8) * 2;
;     bf16x8 b0 = *reinterpret_cast<const bf16x8*>(Kn + KSWZ(r32, cb));
;     bf16x8 b1 = *reinterpret_cast<const bf16x8*>(Kn + KSWZ(32 + r32, cb));
;     p0 = __builtin_amdgcn_mfma_f32_32x32x16_bf16(b0, qr[d0], p0, 0, 0, 0);
;     p1 = __builtin_amdgcn_mfma_f32_32x32x16_bf16(b1, qr[d0], p1, 0, 0, 0); }
; #pragma unroll
;   for (int d1 = 0; d1 < 4; ++d1) { int cb = (d1 * 16 + hi * 8) * 2;
;     bf16x8 b0 = *reinterpret_cast<const bf16x8*>(Kp + KPSWZ(r32, cb));
;     bf16x8 b1 = *reinterpret_cast<const bf16x8*>(Kp + KPSWZ(32 + r32, cb));
;     p0 = __builtin_amdgcn_mfma_f32_32x32x16_bf16(b0, qr[8 + d1], p0, 0, 0, 0);
;     p1 = __builtin_amdgcn_mfma_f32_32x32x16_bf16(b1, qr[8 + d1], p1, 0, 0, 0); }
; template <int D0> __device__ __forceinline__ void pv_one(f32x16& od, int vb, bf16x8 pa0, bf16x8 pa1, bf16x8 pa2, bf16x8 pa3) {
;   const s16x4 l0 = tr_read<v_rd_off(D0, 0, 0)>(vb), h0 = tr_read<v_rd_off(D0, 0, 1)>(vb), l1 = tr_read<v_rd_off(D0, 1, 0)>(vb), h1 = tr_read<v_rd_off(D0, 1, 1)>(vb);
;   const s16x4 l2 = tr_read<v_rd_off(D0, 2, 0)>(vb), h2 = tr_read<v_rd_off(D0, 2, 1)>(vb), l3 = tr_read<v_rd_off(D0, 3, 0)>(vb), h3 = tr_read<v_rd_off(D0, 3, 1)>(vb);
;   asm volatile("s_waitcnt lgkmcnt(0)" ::: "memory"); SBAR();
;     ...
;   od = __builtin_amdgcn_mfma_f32_32x32x16_bf16(pa0, PK(l0, h0), od, 0, 0, 0);
;   od = __builtin_amdgcn_mfma_f32_32x32x16_bf16(pa1, PK(l1, h1), od, 0, 0, 0);
;   od = __builtin_amdgcn_mfma_f32_32x32x16_bf16(pa2, PK(l2, h2), od, 0, 0, 0);
;   od = __builtin_amdgcn_mfma_f32_32x32x16_bf16(pa3, PK(l3, h3), od, 0, 0, 0);
;     ...
; }
; __device__ __forceinline__ void pv_d0(f32x16* o, int vb, bf16x8 pa0, bf16x8 pa1, bf16x8 pa2, bf16x8 pa3) {
;   pv_one<0>(o[0], vb, pa0, pa1, pa2, pa3); pv_one<1>(o[1], vb, pa0, pa1, pa2, pa3); pv_one<2>(o[2], vb, pa0, pa1, pa2, pa3); pv_one<3>(o[3], vb, pa0, pa1, pa2, pa3);
	v_mfma_f32_32x32x16_bf16 v[80:95], v[192:195], v[120:123], v[80:95]
	v_mfma_f32_32x32x16_bf16 v[64:79], v[196:199], v[120:123], v[64:79]
	s_add_u32 s52, s50, 0x20000
	s_addc_u32 s53, s51, 0
	s_lshl_b32 s44, s37, 12
	s_add_u32 s54, s47, s44
	s_addc_u32 s55, s63, 0
	ds_read_b128 v[192:195], v168
	ds_read_b128 v[196:199], v168 offset:4096
	s_waitcnt lgkmcnt(6)
	v_mfma_f32_32x32x16_bf16 v[80:95], v[200:203], v[140:143], v[80:95]
	v_mfma_f32_32x32x16_bf16 v[64:79], v[204:207], v[140:143], v[64:79]
	s_add_u32 s56, s54, 0x20000
	s_addc_u32 s57, s55, 0
	s_lshl_b32 s44, s36, 10
	s_add_u32 s58, s60, s44
	s_addc_u32 s59, s61, 0
	ds_read_b128 v[200:203], v169
	ds_read_b128 v[204:207], v169 offset:4096
	s_waitcnt lgkmcnt(6)
	v_mfma_f32_32x32x16_bf16 v[80:95], v[208:211], v[116:119], v[80:95]
	v_mfma_f32_32x32x16_bf16 v[64:79], v[212:215], v[116:119], v[64:79]
	s_movk_i32 s73, 0x4000
	s_movk_i32 s74, 0x2000
	s_cmp_eq_u32 s65, 0
	s_cselect_b32 s73, s73, 0xc000
	s_cselect_b32 s74, s74, 0xa000
	ds_read_b128 v[208:211], v170
	ds_read_b128 v[212:215], v170 offset:4096
	s_waitcnt lgkmcnt(6)
	v_mfma_f32_32x32x16_bf16 v[80:95], v[216:219], v[112:115], v[80:95]
	v_mfma_f32_32x32x16_bf16 v[64:79], v[220:223], v[112:115], v[64:79]
	s_cmp_eq_u32 s65, 2
	s_cselect_b32 s73, 0xffff0000, s73
	s_cselect_b32 s74, 0xffff4000, s74
	s_cselect_b32 s65, -1, s65
	s_add_i32 s65, s65, 1
	ds_read_b128 v[216:219], v171
	ds_read_b128 v[220:223], v171 offset:4096
	s_waitcnt lgkmcnt(6)
	v_mfma_f32_32x32x16_bf16 v[80:95], v[192:195], v[108:111], v[80:95]
	v_mfma_f32_32x32x16_bf16 v[64:79], v[196:199], v[108:111], v[64:79]
	s_movk_i32 s75, 0x4000
	s_movk_i32 s98, 0x2000
	s_cmp_eq_u32 s72, 0
	s_cselect_b32 s75, s75, 0xc000
	s_cselect_b32 s98, s98, 0xa000
	ds_read_b64_tr_b16 v[192:193], v174 offset:0
	ds_read_b64_tr_b16 v[194:195], v174 offset:2048
	ds_read_b64_tr_b16 v[196:197], v174 offset:4096
	ds_read_b64_tr_b16 v[198:199], v174 offset:6144
	s_waitcnt lgkmcnt(8)
	v_mfma_f32_32x32x16_bf16 v[80:95], v[200:203], v[104:107], v[80:95]
	v_mfma_f32_32x32x16_bf16 v[64:79], v[204:207], v[104:107], v[64:79]
	s_cmp_eq_u32 s72, 2
	s_cselect_b32 s75, 0xffff0000, s75
	s_cselect_b32 s98, 0xffff4000, s98
	s_cselect_b32 s72, -1, s72
	s_add_i32 s72, s72, 1
	ds_read_b64_tr_b16 v[200:201], v174 offset:8192
	ds_read_b64_tr_b16 v[202:203], v174 offset:10240
	ds_read_b64_tr_b16 v[204:205], v174 offset:12288
	ds_read_b64_tr_b16 v[206:207], v174 offset:14336
	s_waitcnt lgkmcnt(10)
	v_mfma_f32_32x32x16_bf16 v[80:95], v[208:211], v[100:103], v[80:95]
	v_mfma_f32_32x32x16_bf16 v[64:79], v[212:215], v[100:103], v[64:79]
	ds_read_b64_tr_b16 v[208:209], v174 offset:512
	ds_read_b64_tr_b16 v[210:211], v174 offset:2560
	ds_read_b64_tr_b16 v[212:213], v174 offset:4608
	ds_read_b64_tr_b16 v[214:215], v174 offset:6656
	s_waitcnt lgkmcnt(12)
	v_mfma_f32_32x32x16_bf16 v[80:95], v[216:219], v[96:99], v[80:95]
	v_mfma_f32_32x32x16_bf16 v[64:79], v[220:223], v[96:99], v[64:79]
	ds_read_b64_tr_b16 v[216:217], v174 offset:8704
	ds_read_b64_tr_b16 v[218:219], v174 offset:10752
	ds_read_b64_tr_b16 v[220:221], v174 offset:12800
	ds_read_b64_tr_b16 v[222:223], v174 offset:14848
	s_waitcnt lgkmcnt(12)
	v_mfma_f32_32x32x16_bf16 v[0:15], v[144:147], v[192:195], v[0:15]
	ds_read_b64_tr_b16 v[192:193], v174 offset:1024
	ds_read_b64_tr_b16 v[194:195], v174 offset:3072
	v_mfma_f32_32x32x16_bf16 v[0:15], v[148:151], v[196:199], v[0:15]
	ds_read_b64_tr_b16 v[196:197], v174 offset:5120
	ds_read_b64_tr_b16 v[198:199], v174 offset:7168
	s_waitcnt lgkmcnt(12)
	v_mfma_f32_32x32x16_bf16 v[0:15], v[152:155], v[200:203], v[0:15]
	ds_read_b64_tr_b16 v[200:201], v174 offset:9216
	ds_read_b64_tr_b16 v[202:203], v174 offset:11264
	v_mfma_f32_32x32x16_bf16 v[0:15], v[156:159], v[204:207], v[0:15]
	ds_read_b64_tr_b16 v[204:205], v174 offset:13312
	ds_read_b64_tr_b16 v[206:207], v174 offset:15360
	s_waitcnt lgkmcnt(12)
	v_mfma_f32_32x32x16_bf16 v[48:63], v[144:147], v[208:211], v[48:63]
	ds_read_b64_tr_b16 v[208:209], v174 offset:1536
	ds_read_b64_tr_b16 v[210:211], v174 offset:3584
	v_mfma_f32_32x32x16_bf16 v[48:63], v[148:151], v[212:215], v[48:63]
	ds_read_b64_tr_b16 v[212:213], v174 offset:5632
	ds_read_b64_tr_b16 v[214:215], v174 offset:7680
	s_waitcnt lgkmcnt(12)
	v_mfma_f32_32x32x16_bf16 v[48:63], v[152:155], v[216:219], v[48:63]
	ds_read_b64_tr_b16 v[216:217], v174 offset:9728
	ds_read_b64_tr_b16 v[218:219], v174 offset:11776
	v_mfma_f32_32x32x16_bf16 v[48:63], v[156:159], v[220:223], v[48:63]
	ds_read_b64_tr_b16 v[220:221], v174 offset:13824
	ds_read_b64_tr_b16 v[222:223], v174 offset:15872
	s_waitcnt lgkmcnt(12)
	v_mfma_f32_32x32x16_bf16 v[32:47], v[144:147], v[192:195], v[32:47]
	v_mfma_f32_32x32x16_bf16 v[32:47], v[148:151], v[196:199], v[32:47]
	s_waitcnt lgkmcnt(8)
	v_mfma_f32_32x32x16_bf16 v[32:47], v[152:155], v[200:203], v[32:47]
	v_mfma_f32_32x32x16_bf16 v[32:47], v[156:159], v[204:207], v[32:47]
	s_waitcnt lgkmcnt(4)
	v_mfma_f32_32x32x16_bf16 v[16:31], v[144:147], v[208:211], v[16:31]
	v_mfma_f32_32x32x16_bf16 v[16:31], v[148:151], v[212:215], v[16:31]
	s_waitcnt lgkmcnt(0)
	v_mfma_f32_32x32x16_bf16 v[16:31], v[152:155], v[216:219], v[16:31]
	v_mfma_f32_32x32x16_bf16 v[16:31], v[156:159], v[220:223], v[16:31]
	s_barrier
; #define SBAR() __builtin_amdgcn_sched_barrier(0)
; #define SLOAD(j) do { const int r0_ = TROW(j); const bf16_t* a_ = KVh + (size_t)(r0_ + sr) * LDKV + sc; const bf16_t* b_ = KVh + (size_t)(r0_ + 32 + sr) * LDKV + sc; \
;     vs0 = ld8(a_ + 128); vs1 = ld8(b_ + 128); ks0 = ld8(a_); ks1 = ld8(b_); kp0 = ld8(KPh + (size_t)(r0_ + pr) * LDKP + pc); } while (0)
; #define SWAIT() asm volatile("s_waitcnt vmcnt(0)" ::: "memory")
; __device__ __forceinline__ void partialSM(f32x16& p0, f32x16& p1, float& m_reg, float& mn, float& alpha) {
;   constexpr float C = SCALE * 1.4426950408889634f;
;   float pmax = p0[0]; for (int r = 1; r < 16; ++r) pmax = fmaxf(pmax, p0[r]); for (int r = 0; r < 16; ++r) pmax = fmaxf(pmax, p1[r]);
;   { auto rr = __builtin_amdgcn_permlane32_swap(__float_as_uint(pmax), __float_as_uint(pmax), false, false);
;     pmax = fmaxf(__uint_as_float(rr[0]), __uint_as_float(rr[1])); }
;   if (__builtin_expect(__all(pmax - m_reg <= THR / SCALE), 1)) { mn = m_reg; alpha = 1.f; }
;   else { mn = fmaxf(m_reg, pmax); alpha = __builtin_amdgcn_exp2f((m_reg - mn) * C); m_reg = mn; }
;   float mnC = -mn * C;
;   for (int r = 0; r < 16; ++r) p0[r] = fmaf(p0[r], C, mnC); for (int r = 0; r < 16; ++r) p1[r] = fmaf(p1[r], C, mnC);
;   for (int r = 0; r < 16; ++r) p0[r] = __builtin_amdgcn_exp2f(p0[r]);
; }
; __device__ __forceinline__ void finishSM(f32x16& p0, f32x16& p1, float alpha, float& l_reg, bf16x8& pa0, bf16x8& pa1, bf16x8& pa2, bf16x8& pa3) {
;   for (int r = 0; r < 16; ++r) p1[r] = __builtin_amdgcn_exp2f(p1[r]);
;   float ps = 0; for (int r = 0; r < 16; ++r) ps += p0[r]; for (int r = 0; r < 16; ++r) ps += p1[r];
;   { auto rr = __builtin_amdgcn_permlane32_swap(__float_as_uint(ps), __float_as_uint(ps), false, false);
;     ps = __uint_as_float(rr[0]) + __uint_as_float(rr[1]); }
;   l_reg = l_reg * alpha + ps;
;     ...
;   PK4(p0, 0, pa0); PK4(p0, 8, pa1); PK4(p1, 0, pa2); PK4(p1, 8, pa3);
; __device__ __forceinline__ void attn_unit(const bf16_t* __restrict__ Qb, const bf16_t* __restrict__ KV, const bf16_t* __restrict__ KP, bf16_t* __restrict__ Ob, ...
;     ...
;     SBAR(); qkt(pA0, pA1, KN_lds, KP_lds, qr, r32, hi);
;     finishSM(pB0, pB1, alB, l_reg, pa0, pa1, pa2, pa3); SBAR();
;     SLOAD(j + 2); SBAR();
;     pv_d0(o, vb0 + SHM_V, pa0, pa1, pa2, pa3); partialSM(pA0, pA1, m_reg, mnA, alA);
;     __syncthreads(); SWAIT(); SWRITE(1);
;     RESC(alA); __syncthreads();
	v_add_u32_e32 v160, s73, v160
	v_add_u32_e32 v161, s73, v161
	v_add_u32_e32 v162, s73, v162
	v_add_u32_e32 v163, s73, v163
	v_add_u32_e32 v164, s73, v164
	v_add_u32_e32 v165, s73, v165
	v_add_u32_e32 v166, s73, v166
	v_add_u32_e32 v167, s73, v167
	v_add_u32_e32 v168, s74, v168
	v_add_u32_e32 v169, s74, v169
	v_add_u32_e32 v170, s74, v170
	v_add_u32_e32 v171, s74, v171
	ds_read_b128 v[192:195], v160
	ds_read_b128 v[196:199], v160 offset:8192
	ds_read_b128 v[200:203], v161
	ds_read_b128 v[204:207], v161 offset:8192
	ds_read_b128 v[208:211], v162
	ds_read_b128 v[212:215], v162 offset:8192
	ds_read_b128 v[216:219], v163
	ds_read_b128 v[220:223], v163 offset:8192
	v_max3_f32 v250, v80, v81, v82
	v_max3_f32 v250, v250, v83, v84
	v_max3_f32 v250, v250, v85, v86
	v_max3_f32 v250, v250, v87, v88
	v_max3_f32 v250, v250, v89, v90
	v_max3_f32 v250, v250, v91, v92
	v_max3_f32 v250, v250, v93, v94
	v_max3_f32 v250, v250, v95, v64
	v_max3_f32 v250, v250, v65, v66
	v_max3_f32 v250, v250, v67, v68
	v_max3_f32 v250, v250, v69, v70
	v_max3_f32 v250, v250, v71, v72
	v_max3_f32 v250, v250, v73, v74
	v_max3_f32 v250, v250, v75, v76
	v_max3_f32 v250, v250, v77, v78
	v_max3_f32 v250, v250, v79, v79
	v_cmp_lt_f32_e64 vcc, s64, |v250|
	s_waitcnt vmcnt(0)
	ds_write_b128 v246, v[232:235]
	ds_write_b128 v246, v[236:239] offset:8192
	ds_write_b128 v248, v[240:243]
	ds_write_b128 v245, v[224:227]
	ds_write_b128 v245, v[228:231] offset:8192
	v_add_u32_e32 v246, s75, v246
	v_add_u32_e32 v248, s98, v248
	global_load_dwordx4 v[232:235], v180, s[50:51]
	global_load_dwordx4 v[236:239], v180, s[52:53]
	global_load_dwordx4 v[224:227], v180, s[54:55] offset:256
	global_load_dwordx4 v[228:231], v180, s[56:57] offset:256
	global_load_dwordx4 v[240:243], v181, s[58:59]
	s_cmp_lg_u32 s62, 0
	s_cbranch_scc1 .Lpp_safe_Bb
	s_cbranch_vccnz .Lpp_sw_Bb
	v_exp_f32_e32 v80, v80
	v_exp_f32_e32 v81, v81
	v_exp_f32_e32 v82, v82
	v_exp_f32_e32 v83, v83
	v_exp_f32_e32 v84, v84
	v_exp_f32_e32 v85, v85
	v_exp_f32_e32 v86, v86
	v_exp_f32_e32 v87, v87
	v_exp_f32_e32 v88, v88
	v_exp_f32_e32 v89, v89
	v_exp_f32_e32 v90, v90
	v_exp_f32_e32 v91, v91
	v_exp_f32_e32 v92, v92
	v_exp_f32_e32 v93, v93
	v_exp_f32_e32 v94, v94
	v_exp_f32_e32 v95, v95
	v_exp_f32_e32 v64, v64
	v_exp_f32_e32 v65, v65
	v_exp_f32_e32 v66, v66
	v_exp_f32_e32 v67, v67
	v_exp_f32_e32 v68, v68
	v_exp_f32_e32 v69, v69
	v_exp_f32_e32 v70, v70
	v_exp_f32_e32 v71, v71
	v_exp_f32_e32 v72, v72
	v_exp_f32_e32 v73, v73
	v_exp_f32_e32 v74, v74
	v_exp_f32_e32 v75, v75
	v_exp_f32_e32 v76, v76
	v_exp_f32_e32 v77, v77
	v_exp_f32_e32 v78, v78
	v_exp_f32_e32 v79, v79
	v_add_f32_e32 v249, v80, v81
	v_add_f32_e32 v250, v82, v83
	v_add_f32_e32 v251, v84, v85
	v_add_f32_e32 v182, v86, v87
	v_add_f32_e32 v249, v88, v249
	v_add_f32_e32 v250, v89, v250
	v_add_f32_e32 v251, v90, v251
	v_add_f32_e32 v182, v91, v182
	v_add_f32_e32 v249, v92, v249
	v_add_f32_e32 v250, v93, v250
	v_add_f32_e32 v251, v94, v251
	v_add_f32_e32 v182, v95, v182
	v_add_f32_e32 v249, v64, v249
	v_add_f32_e32 v250, v65, v250
	v_add_f32_e32 v251, v66, v251
	v_add_f32_e32 v182, v67, v182
	v_add_f32_e32 v249, v68, v249
	v_add_f32_e32 v250, v69, v250
	v_add_f32_e32 v251, v70, v251
	v_add_f32_e32 v182, v71, v182
	v_add_f32_e32 v249, v72, v249
	v_add_f32_e32 v250, v73, v250
	v_add_f32_e32 v251, v74, v251
	v_add_f32_e32 v182, v75, v182
	v_add_f32_e32 v249, v76, v249
	v_add_f32_e32 v250, v77, v250
	v_add_f32_e32 v251, v78, v251
	v_add_f32_e32 v182, v79, v182
	v_add_f32_e32 v249, v249, v250
	v_add_f32_e32 v251, v251, v182
	v_add_f32_e32 v249, v249, v251
	v_add_f32_e32 v176, v176, v249
	v_cvt_pk_bf16_f32 v144, v80, v81
	v_cvt_pk_bf16_f32 v145, v82, v83
	v_cvt_pk_bf16_f32 v146, v84, v85
	v_cvt_pk_bf16_f32 v147, v86, v87
	v_cvt_pk_bf16_f32 v148, v88, v89
	v_cvt_pk_bf16_f32 v149, v90, v91
	v_cvt_pk_bf16_f32 v150, v92, v93
	v_cvt_pk_bf16_f32 v151, v94, v95
	v_cvt_pk_bf16_f32 v152, v64, v65
	v_cvt_pk_bf16_f32 v153, v66, v67
	v_cvt_pk_bf16_f32 v154, v68, v69
	v_cvt_pk_bf16_f32 v155, v70, v71
	v_cvt_pk_bf16_f32 v156, v72, v73
	v_cvt_pk_bf16_f32 v157, v74, v75
	v_cvt_pk_bf16_f32 v158, v76, v77
	v_cvt_pk_bf16_f32 v159, v78, v79
; #define SBAR() __builtin_amdgcn_sched_barrier(0)
; #define SLOAD(j) do { const int r0_ = TROW(j); const bf16_t* a_ = KVh + (size_t)(r0_ + sr) * LDKV + sc; const bf16_t* b_ = KVh + (size_t)(r0_ + 32 + sr) * LDKV + sc; \
;     vs0 = ld8(a_ + 128); vs1 = ld8(b_ + 128); ks0 = ld8(a_); ks1 = ld8(b_); kp0 = ld8(KPh + (size_t)(r0_ + pr) * LDKP + pc); } while (0)
; #define SWRITE(b) do { *(bf16x8*)(V_lds + (b) * SHM_V + vst0) = vs0; *(bf16x8*)(V_lds + (b) * SHM_V + vst1) = vs1; const int kc = sc * 2; \
;     *(bf16x8*)(KN_lds + (b) * SHM_KN + KSWZ(sr, kc)) = ks0; *(bf16x8*)(KN_lds + (b) * SHM_KN + KSWZ(32 + sr, kc)) = ks1; \
;     *(bf16x8*)(KP_lds + (b) * SHM_KP + KPSWZ(pr, pc * 2)) = kp0; } while (0)
; #define SWAIT() asm volatile("s_waitcnt vmcnt(0)" ::: "memory")
; __device__ __forceinline__ void qkt(f32x16& p0, f32x16& p1, const char* Kn, const char* Kp, const bf16x8* qr, int r32, int hi) {
;   p0 = f32x16{}; p1 = f32x16{};
; #pragma unroll
;   for (int d0 = 0; d0 < 8; ++d0) { int cb = (d0 * 16 + hi * 8) * 2;
;     bf16x8 b0 = *reinterpret_cast<const bf16x8*>(Kn + KSWZ(r32, cb));
;     bf16x8 b1 = *reinterpret_cast<const bf16x8*>(Kn + KSWZ(32 + r32, cb));
;     p0 = __builtin_amdgcn_mfma_f32_32x32x16_bf16(b0, qr[d0], p0, 0, 0, 0);
;     p1 = __builtin_amdgcn_mfma_f32_32x32x16_bf16(b1, qr[d0], p1, 0, 0, 0); }
; #pragma unroll
;   for (int d1 = 0; d1 < 4; ++d1) { int cb = (d1 * 16 + hi * 8) * 2;
;     bf16x8 b0 = *reinterpret_cast<const bf16x8*>(Kp + KPSWZ(r32, cb));
;     bf16x8 b1 = *reinterpret_cast<const bf16x8*>(Kp + KPSWZ(32 + r32, cb));
;     p0 = __builtin_amdgcn_mfma_f32_32x32x16_bf16(b0, qr[8 + d1], p0, 0, 0, 0);
;     p1 = __builtin_amdgcn_mfma_f32_32x32x16_bf16(b1, qr[8 + d1], p1, 0, 0, 0); }
; __device__ __forceinline__ void attn_unit(const bf16_t* __restrict__ Qb, const bf16_t* __restrict__ KV, const bf16_t* __restrict__ KP, bf16_t* __restrict__ Ob, ...
;     ...
;     SBAR(); qkt(pA0, pA1, KN_lds, KP_lds, qr, r32, hi);
;     finishSM(pB0, pB1, alB, l_reg, pa0, pa1, pa2, pa3); SBAR();
;     SLOAD(j + 2); SBAR();
;     pv_d0(o, vb0 + SHM_V, pa0, pa1, pa2, pa3); partialSM(pA0, pA1, m_reg, mnA, alA);
;     __syncthreads(); SWAIT(); SWRITE(1);
;     RESC(alA); __syncthreads();
;   }
.Lpp_send_Bb:
	s_add_i32 s11, s11, 1
	s_cmp_eq_u32 s11, 68
	s_cbranch_scc1 .Lpp_last
	s_waitcnt lgkmcnt(6)
	v_mfma_f32_32x32x16_bf16 v[80:95], v[192:195], v[136:139], 0
	v_mfma_f32_32x32x16_bf16 v[64:79], v[196:199], v[136:139], 0
	s_add_i32 s36, s35, 3
	s_min_u32 s36, s36, 67
	s_lshl_b32 s44, s36, 6
	s_add_i32 s45, s31, s44
	s_add_i32 s46, s24, s44
	ds_read_b128 v[192:195], v164
	ds_read_b128 v[196:199], v164 offset:8192
	s_waitcnt lgkmcnt(6)
	v_mfma_f32_32x32x16_bf16 v[80:95], v[200:203], v[132:135], v[80:95]
	v_mfma_f32_32x32x16_bf16 v[64:79], v[204:207], v[132:135], v[64:79]
	s_add_i32 s46, s46, 0xffffff00
	s_cmp_lt_u32 s36, 4
	s_cselect_b32 s36, s45, s46
	s_add_i32 s37, s35, 1
	s_min_u32 s37, s37, 67
	ds_read_b128 v[200:203], v165
	ds_read_b128 v[204:207], v165 offset:8192
	s_waitcnt lgkmcnt(6)
	v_mfma_f32_32x32x16_bf16 v[80:95], v[208:211], v[128:131], v[80:95]
	v_mfma_f32_32x32x16_bf16 v[64:79], v[212:215], v[128:131], v[64:79]
	s_lshl_b32 s44, s37, 6
	s_add_i32 s45, s31, s44
	s_add_i32 s46, s24, s44
	s_add_i32 s46, s46, 0xffffff00
	s_cmp_lt_u32 s37, 4
	ds_read_b128 v[208:211], v166
	ds_read_b128 v[212:215], v166 offset:8192
	s_waitcnt lgkmcnt(6)
	v_mfma_f32_32x32x16_bf16 v[80:95], v[216:219], v[124:127], v[80:95]
	v_mfma_f32_32x32x16_bf16 v[64:79], v[220:223], v[124:127], v[64:79]
	s_cselect_b32 s37, s45, s46
	s_add_i32 s35, s35, 1
	s_lshl_b32 s44, s36, 12
	s_add_u32 s50, s47, s44
	s_addc_u32 s51, s63, 0
	ds_read_b128 v[216:219], v167
	ds_read_b128 v[220:223], v167 offset:8192
	s_waitcnt lgkmcnt(6)
	v_mfma_f32_32x32x16_bf16 v[80:95], v[192:195], v[120:123], v[80:95]
	v_mfma_f32_32x32x16_bf16 v[64:79], v[196:199], v[120:123], v[64:79]
	s_add_u32 s52, s50, 0x20000
	s_addc_u32 s53, s51, 0
	s_lshl_b32 s44, s37, 12
	s_add_u32 s54, s47, s44
	s_addc_u32 s55, s63, 0
	ds_read_b128 v[192:195], v168
	ds_read_b128 v[196:199], v168 offset:4096
	s_waitcnt lgkmcnt(6)
	v_mfma_f32_32x32x16_bf16 v[80:95], v[200:203], v[140:143], v[80:95]
	v_mfma_f32_32x32x16_bf16 v[64:79], v[204:207], v[140:143], v[64:79]
	s_add_u32 s56, s54, 0x20000
	s_addc_u32 s57, s55, 0
	s_lshl_b32 s44, s36, 10
	s_add_u32 s58, s60, s44
	s_addc_u32 s59, s61, 0
	ds_read_b128 v[200:203], v169
	ds_read_b128 v[204:207], v169 offset:4096
	s_waitcnt lgkmcnt(6)
	v_mfma_f32_32x32x16_bf16 v[80:95], v[208:211], v[116:119], v[80:95]
	v_mfma_f32_32x32x16_bf16 v[64:79], v[212:215], v[116:119], v[64:79]
	s_movk_i32 s73, 0x4000
	s_movk_i32 s74, 0x2000
	s_cmp_eq_u32 s65, 0
	s_cselect_b32 s73, s73, 0xc000
	s_cselect_b32 s74, s74, 0xa000
	ds_read_b128 v[208:211], v170
	ds_read_b128 v[212:215], v170 offset:4096
	s_waitcnt lgkmcnt(6)
	v_mfma_f32_32x32x16_bf16 v[80:95], v[216:219], v[112:115], v[80:95]
	v_mfma_f32_32x32x16_bf16 v[64:79], v[220:223], v[112:115], v[64:79]
	s_cmp_eq_u32 s65, 2
	s_cselect_b32 s73, 0xffff0000, s73
	s_cselect_b32 s74, 0xffff4000, s74
	s_cselect_b32 s65, -1, s65
	s_add_i32 s65, s65, 1
	ds_read_b128 v[216:219], v171
	ds_read_b128 v[220:223], v171 offset:4096
	s_waitcnt lgkmcnt(6)
	v_mfma_f32_32x32x16_bf16 v[80:95], v[192:195], v[108:111], v[80:95]
	v_mfma_f32_32x32x16_bf16 v[64:79], v[196:199], v[108:111], v[64:79]
	s_movk_i32 s75, 0x4000
	s_movk_i32 s98, 0x2000
	s_cmp_eq_u32 s72, 0
	s_cselect_b32 s75, s75, 0xc000
	s_cselect_b32 s98, s98, 0xa000
	ds_read_b64_tr_b16 v[192:193], v174 offset:16384
	ds_read_b64_tr_b16 v[194:195], v174 offset:18432
	ds_read_b64_tr_b16 v[196:197], v174 offset:20480
	ds_read_b64_tr_b16 v[198:199], v174 offset:22528
	s_waitcnt lgkmcnt(8)
	v_mfma_f32_32x32x16_bf16 v[80:95], v[200:203], v[104:107], v[80:95]
	v_mfma_f32_32x32x16_bf16 v[64:79], v[204:207], v[104:107], v[64:79]
	s_cmp_eq_u32 s72, 2
	s_cselect_b32 s75, 0xffff0000, s75
	s_cselect_b32 s98, 0xffff4000, s98
	s_cselect_b32 s72, -1, s72
	s_add_i32 s72, s72, 1
	ds_read_b64_tr_b16 v[200:201], v174 offset:24576
	ds_read_b64_tr_b16 v[202:203], v174 offset:26624
	ds_read_b64_tr_b16 v[204:205], v174 offset:28672
	ds_read_b64_tr_b16 v[206:207], v174 offset:30720
	s_waitcnt lgkmcnt(10)
	v_mfma_f32_32x32x16_bf16 v[80:95], v[208:211], v[100:103], v[80:95]
	v_mfma_f32_32x32x16_bf16 v[64:79], v[212:215], v[100:103], v[64:79]
	ds_read_b64_tr_b16 v[208:209], v174 offset:16896
	ds_read_b64_tr_b16 v[210:211], v174 offset:18944
	ds_read_b64_tr_b16 v[212:213], v174 offset:20992
	ds_read_b64_tr_b16 v[214:215], v174 offset:23040
	s_waitcnt lgkmcnt(12)
	v_mfma_f32_32x32x16_bf16 v[80:95], v[216:219], v[96:99], v[80:95]
	v_mfma_f32_32x32x16_bf16 v[64:79], v[220:223], v[96:99], v[64:79]
	ds_read_b64_tr_b16 v[216:217], v174 offset:25088
	ds_read_b64_tr_b16 v[218:219], v174 offset:27136
	ds_read_b64_tr_b16 v[220:221], v174 offset:29184
	ds_read_b64_tr_b16 v[222:223], v174 offset:31232
	s_waitcnt lgkmcnt(12)
	v_mfma_f32_32x32x16_bf16 v[0:15], v[144:147], v[192:195], v[0:15]
	ds_read_b64_tr_b16 v[192:193], v174 offset:17408
	ds_read_b64_tr_b16 v[194:195], v174 offset:19456
	v_mfma_f32_32x32x16_bf16 v[0:15], v[148:151], v[196:199], v[0:15]
	ds_read_b64_tr_b16 v[196:197], v174 offset:21504
	ds_read_b64_tr_b16 v[198:199], v174 offset:23552
	s_waitcnt lgkmcnt(12)
	v_mfma_f32_32x32x16_bf16 v[0:15], v[152:155], v[200:203], v[0:15]
	ds_read_b64_tr_b16 v[200:201], v174 offset:25600
	ds_read_b64_tr_b16 v[202:203], v174 offset:27648
	v_mfma_f32_32x32x16_bf16 v[0:15], v[156:159], v[204:207], v[0:15]
	ds_read_b64_tr_b16 v[204:205], v174 offset:29696
	ds_read_b64_tr_b16 v[206:207], v174 offset:31744
	s_waitcnt lgkmcnt(12)
	v_mfma_f32_32x32x16_bf16 v[48:63], v[144:147], v[208:211], v[48:63]
	ds_read_b64_tr_b16 v[208:209], v174 offset:17920
	ds_read_b64_tr_b16 v[210:211], v174 offset:19968
	v_mfma_f32_32x32x16_bf16 v[48:63], v[148:151], v[212:215], v[48:63]
	ds_read_b64_tr_b16 v[212:213], v174 offset:22016
	ds_read_b64_tr_b16 v[214:215], v174 offset:24064
	s_waitcnt lgkmcnt(12)
	v_mfma_f32_32x32x16_bf16 v[48:63], v[152:155], v[216:219], v[48:63]
	ds_read_b64_tr_b16 v[216:217], v174 offset:26112
	ds_read_b64_tr_b16 v[218:219], v174 offset:28160
	v_mfma_f32_32x32x16_bf16 v[48:63], v[156:159], v[220:223], v[48:63]
	ds_read_b64_tr_b16 v[220:221], v174 offset:30208
	ds_read_b64_tr_b16 v[222:223], v174 offset:32256
	s_waitcnt lgkmcnt(12)
	v_mfma_f32_32x32x16_bf16 v[32:47], v[144:147], v[192:195], v[32:47]
	v_mfma_f32_32x32x16_bf16 v[32:47], v[148:151], v[196:199], v[32:47]
	s_waitcnt lgkmcnt(8)
	v_mfma_f32_32x32x16_bf16 v[32:47], v[152:155], v[200:203], v[32:47]
	v_mfma_f32_32x32x16_bf16 v[32:47], v[156:159], v[204:207], v[32:47]
	s_waitcnt lgkmcnt(4)
	v_mfma_f32_32x32x16_bf16 v[16:31], v[144:147], v[208:211], v[16:31]
	v_mfma_f32_32x32x16_bf16 v[16:31], v[148:151], v[212:215], v[16:31]
	s_waitcnt lgkmcnt(0)
	v_mfma_f32_32x32x16_bf16 v[16:31], v[152:155], v[216:219], v[16:31]
	v_mfma_f32_32x32x16_bf16 v[16:31], v[156:159], v[220:223], v[16:31]
	s_branch .Lpp_loop

; #define SBAR() __builtin_amdgcn_sched_barrier(0)
; #define SLOAD(j) do { const int r0_ = TROW(j); const bf16_t* a_ = KVh + (size_t)(r0_ + sr) * LDKV + sc; const bf16_t* b_ = KVh + (size_t)(r0_ + 32 + sr) * LDKV + sc; \
;     vs0 = ld8(a_ + 128); vs1 = ld8(b_ + 128); ks0 = ld8(a_); ks1 = ld8(b_); kp0 = ld8(KPh + (size_t)(r0_ + pr) * LDKP + pc); } while (0)
; #define SWRITE(b) do { *(bf16x8*)(V_lds + (b) * SHM_V + vst0) = vs0; *(bf16x8*)(V_lds + (b) * SHM_V + vst1) = vs1; const int kc = sc * 2; \
;     *(bf16x8*)(KN_lds + (b) * SHM_KN + KSWZ(sr, kc)) = ks0; *(bf16x8*)(KN_lds + (b) * SHM_KN + KSWZ(32 + sr, kc)) = ks1; \
;     *(bf16x8*)(KP_lds + (b) * SHM_KP + KPSWZ(pr, pc * 2)) = kp0; } while (0)
; #define SWAIT() asm volatile("s_waitcnt vmcnt(0)" ::: "memory")
; __device__ __forceinline__ void qkt(f32x16& p0, f32x16& p1, const char* Kn, const char* Kp, const bf16x8* qr, int r32, int hi) {
;   p0 = f32x16{}; p1 = f32x16{};
; #pragma unroll
;   for (int d0 = 0; d0 < 8; ++d0) { int cb = (d0 * 16 + hi * 8) * 2;
;     bf16x8 b0 = *reinterpret_cast<const bf16x8*>(Kn + KSWZ(r32, cb));
;     bf16x8 b1 = *reinterpret_cast<const bf16x8*>(Kn + KSWZ(32 + r32, cb));
;     p0 = __builtin_amdgcn_mfma_f32_32x32x16_bf16(b0, qr[d0], p0, 0, 0, 0);
;     p1 = __builtin_amdgcn_mfma_f32_32x32x16_bf16(b1, qr[d0], p1, 0, 0, 0); }
; #pragma unroll
;   for (int d1 = 0; d1 < 4; ++d1) { int cb = (d1 * 16 + hi * 8) * 2;
;     bf16x8 b0 = *reinterpret_cast<const bf16x8*>(Kp + KPSWZ(r32, cb));
;     bf16x8 b1 = *reinterpret_cast<const bf16x8*>(Kp + KPSWZ(32 + r32, cb));
;     p0 = __builtin_amdgcn_mfma_f32_32x32x16_bf16(b0, qr[8 + d1], p0, 0, 0, 0);
;     p1 = __builtin_amdgcn_mfma_f32_32x32x16_bf16(b1, qr[8 + d1], p1, 0, 0, 0); }
; __device__ __forceinline__ void attn_unit(const bf16_t* __restrict__ Qb, const bf16_t* __restrict__ KV, const bf16_t* __restrict__ KP, bf16_t* __restrict__ Ob, ...
;     ...
;   for (int j = 1; j + 1 < NT; j += 2) {
;     SBAR(); qkt(pB0, pB1, KN_lds + SHM_KN, KP_lds + SHM_KP, qr, r32, hi);
;     finishSM(pA0, pA1, alA, l_reg, pa0, pa1, pa2, pa3); SBAR();
;     SLOAD(j + 1); SBAR();
;     pv_d0(o, vb0, pa0, pa1, pa2, pa3); partialSM(pB0, pB1, m_reg, mnB, alB);
;     __syncthreads(); SWAIT(); SWRITE(0);
;     RESC(alB); __syncthreads();
.Lpp_ga:
	ds_read_b128 v[192:195], v160
	ds_read_b128 v[196:199], v160 offset:8192
	ds_read_b128 v[200:203], v161
	ds_read_b128 v[204:207], v161 offset:8192
	ds_read_b128 v[208:211], v162
	ds_read_b128 v[212:215], v162 offset:8192
	ds_read_b128 v[216:219], v163
	ds_read_b128 v[220:223], v163 offset:8192
	s_waitcnt lgkmcnt(6)
	v_mfma_f32_32x32x16_bf16 v[80:95], v[192:195], v[136:139], 0
	v_mfma_f32_32x32x16_bf16 v[64:79], v[196:199], v[136:139], 0
	s_add_i32 s36, s35, 3
	s_min_u32 s36, s36, 67
	s_lshl_b32 s44, s36, 6
	s_add_i32 s45, s31, s44
	s_add_i32 s46, s24, s44
	ds_read_b128 v[192:195], v164
	ds_read_b128 v[196:199], v164 offset:8192
	s_waitcnt lgkmcnt(6)
	v_mfma_f32_32x32x16_bf16 v[80:95], v[200:203], v[132:135], v[80:95]
	v_mfma_f32_32x32x16_bf16 v[64:79], v[204:207], v[132:135], v[64:79]
	s_add_i32 s46, s46, 0xffffff00
	s_cmp_lt_u32 s36, 4
	s_cselect_b32 s36, s45, s46
	s_add_i32 s37, s35, 1
	s_min_u32 s37, s37, 67
	ds_read_b128 v[200:203], v165
	ds_read_b128 v[204:207], v165 offset:8192
	s_waitcnt lgkmcnt(6)
	v_mfma_f32_32x32x16_bf16 v[80:95], v[208:211], v[128:131], v[80:95]
	v_mfma_f32_32x32x16_bf16 v[64:79], v[212:215], v[128:131], v[64:79]
	s_lshl_b32 s44, s37, 6
	s_add_i32 s45, s31, s44
	s_add_i32 s46, s24, s44
	s_add_i32 s46, s46, 0xffffff00
	s_cmp_lt_u32 s37, 4
	ds_read_b128 v[208:211], v166
	ds_read_b128 v[212:215], v166 offset:8192
	s_waitcnt lgkmcnt(6)
	v_mfma_f32_32x32x16_bf16 v[80:95], v[216:219], v[124:127], v[80:95]
	v_mfma_f32_32x32x16_bf16 v[64:79], v[220:223], v[124:127], v[64:79]
	s_cselect_b32 s37, s45, s46
	s_add_i32 s35, s35, 1
	s_lshl_b32 s44, s36, 12
	s_add_u32 s50, s47, s44
	s_addc_u32 s51, s63, 0
	ds_read_b128 v[216:219], v167
	ds_read_b128 v[220:223], v167 offset:8192
	s_waitcnt lgkmcnt(6)
	v_mfma_f32_32x32x16_bf16 v[80:95], v[192:195], v[120:123], v[80:95]
	v_mfma_f32_32x32x16_bf16 v[64:79], v[196:199], v[120:123], v[64:79]
	s_add_u32 s52, s50, 0x20000
	s_addc_u32 s53, s51, 0
	s_lshl_b32 s44, s37, 12
	s_add_u32 s54, s47, s44
	s_addc_u32 s55, s63, 0
	ds_read_b128 v[192:195], v168
	ds_read_b128 v[196:199], v168 offset:4096
	s_waitcnt lgkmcnt(6)
	v_mfma_f32_32x32x16_bf16 v[80:95], v[200:203], v[140:143], v[80:95]
	v_mfma_f32_32x32x16_bf16 v[64:79], v[204:207], v[140:143], v[64:79]
	s_add_u32 s56, s54, 0x20000
	s_addc_u32 s57, s55, 0
	s_lshl_b32 s44, s36, 10
	s_add_u32 s58, s60, s44
	s_addc_u32 s59, s61, 0
	ds_read_b128 v[200:203], v169
	ds_read_b128 v[204:207], v169 offset:4096
	s_waitcnt lgkmcnt(6)
	v_mfma_f32_32x32x16_bf16 v[80:95], v[208:211], v[116:119], v[80:95]
	v_mfma_f32_32x32x16_bf16 v[64:79], v[212:215], v[116:119], v[64:79]
	s_movk_i32 s73, 0x4000
	s_movk_i32 s74, 0x2000
	s_cmp_eq_u32 s65, 0
	s_cselect_b32 s73, s73, 0xc000
	s_cselect_b32 s74, s74, 0xa000
	ds_read_b128 v[208:211], v170
	ds_read_b128 v[212:215], v170 offset:4096
	s_waitcnt lgkmcnt(6)
	v_mfma_f32_32x32x16_bf16 v[80:95], v[216:219], v[112:115], v[80:95]
	v_mfma_f32_32x32x16_bf16 v[64:79], v[220:223], v[112:115], v[64:79]
	s_cmp_eq_u32 s65, 2
	s_cselect_b32 s73, 0xffff0000, s73
	s_cselect_b32 s74, 0xffff4000, s74
	s_cselect_b32 s65, -1, s65
	s_add_i32 s65, s65, 1
	ds_read_b128 v[216:219], v171
	ds_read_b128 v[220:223], v171 offset:4096
	s_waitcnt lgkmcnt(6)
	v_mfma_f32_32x32x16_bf16 v[80:95], v[192:195], v[108:111], v[80:95]
	v_mfma_f32_32x32x16_bf16 v[64:79], v[196:199], v[108:111], v[64:79]
	s_movk_i32 s75, 0x4000
	s_movk_i32 s98, 0x2000
	s_cmp_eq_u32 s72, 0
	s_cselect_b32 s75, s75, 0xc000
	s_cselect_b32 s98, s98, 0xa000
	s_waitcnt lgkmcnt(4)
	v_mfma_f32_32x32x16_bf16 v[80:95], v[200:203], v[104:107], v[80:95]
	v_mfma_f32_32x32x16_bf16 v[64:79], v[204:207], v[104:107], v[64:79]
	s_cmp_eq_u32 s72, 2
	s_cselect_b32 s75, 0xffff0000, s75
	s_cselect_b32 s98, 0xffff4000, s98
	s_cselect_b32 s72, -1, s72
	s_add_i32 s72, s72, 1
	s_waitcnt lgkmcnt(2)
	v_mfma_f32_32x32x16_bf16 v[80:95], v[208:211], v[100:103], v[80:95]
	v_mfma_f32_32x32x16_bf16 v[64:79], v[212:215], v[100:103], v[64:79]
	s_waitcnt lgkmcnt(0)
	v_mfma_f32_32x32x16_bf16 v[80:95], v[216:219], v[96:99], v[80:95]
	v_mfma_f32_32x32x16_bf16 v[64:79], v[220:223], v[96:99], v[64:79]
	s_nop 7
	s_nop 7
	s_nop 7
.Lpp_aloop:
	v_max3_f32 v250, v80, v81, v82
	v_max3_f32 v250, v250, v83, v84
	v_max3_f32 v250, v250, v85, v86
	v_max3_f32 v250, v250, v87, v88
	v_max3_f32 v250, v250, v89, v90
	v_max3_f32 v250, v250, v91, v92
	v_max3_f32 v250, v250, v93, v94
	v_max3_f32 v250, v250, v95, v64
	v_max3_f32 v250, v250, v65, v66
	v_max3_f32 v250, v250, v67, v68
	v_max3_f32 v250, v250, v69, v70
	v_max3_f32 v250, v250, v71, v72
	v_max3_f32 v250, v250, v73, v74
	v_max3_f32 v250, v250, v75, v76
	v_max3_f32 v250, v250, v77, v78
	v_max3_f32 v250, v250, v79, v79
	v_cmp_lt_f32_e64 vcc, s64, |v250|
	s_waitcnt vmcnt(0)
	ds_write_b128 v246, v[232:235]
	ds_write_b128 v246, v[236:239] offset:8192
	ds_write_b128 v248, v[240:243]
	ds_write_b128 v244, v[224:227]
	ds_write_b128 v244, v[228:231] offset:8192
	v_add_u32_e32 v246, s75, v246
	v_add_u32_e32 v248, s98, v248
	global_load_dwordx4 v[232:235], v180, s[50:51]
	global_load_dwordx4 v[236:239], v180, s[52:53]
	global_load_dwordx4 v[224:227], v180, s[54:55] offset:256
	global_load_dwordx4 v[228:231], v180, s[56:57] offset:256
	global_load_dwordx4 v[240:243], v181, s[58:59]
	s_cmp_lg_u32 s62, 0
	s_cbranch_scc1 .Lpp_safe_Aa
	s_cbranch_vccnz .Lpp_sw_Aa
; __device__ __forceinline__ void finishSM(f32x16& p0, f32x16& p1, float alpha, float& l_reg, bf16x8& pa0, bf16x8& pa1, bf16x8& pa2, bf16x8& pa3) {
;   for (int r = 0; r < 16; ++r) p1[r] = __builtin_amdgcn_exp2f(p1[r]);
;   float ps = 0; for (int r = 0; r < 16; ++r) ps += p0[r]; for (int r = 0; r < 16; ++r) ps += p1[r];
;   { auto rr = __builtin_amdgcn_permlane32_swap(__float_as_uint(ps), __float_as_uint(ps), false, false);
;     ps = __uint_as_float(rr[0]) + __uint_as_float(rr[1]); }
;   l_reg = l_reg * alpha + ps;
;     ...
;   PK4(p0, 0, pa0); PK4(p0, 8, pa1); PK4(p1, 0, pa2); PK4(p1, 8, pa3);
;     ...
; }
; __device__ __forceinline__ void qkt(f32x16& p0, f32x16& p1, const char* Kn, const char* Kp, const bf16x8* qr, int r32, int hi) {
;   p0 = f32x16{}; p1 = f32x16{};
; #pragma unroll
;   for (int d0 = 0; d0 < 8; ++d0) { int cb = (d0 * 16 + hi * 8) * 2;
;     bf16x8 b0 = *reinterpret_cast<const bf16x8*>(Kn + KSWZ(r32, cb));
;     bf16x8 b1 = *reinterpret_cast<const bf16x8*>(Kn + KSWZ(32 + r32, cb));
;     p0 = __builtin_amdgcn_mfma_f32_32x32x16_bf16(b0, qr[d0], p0, 0, 0, 0);
;     p1 = __builtin_amdgcn_mfma_f32_32x32x16_bf16(b1, qr[d0], p1, 0, 0, 0); }
; #pragma unroll
;   for (int d1 = 0; d1 < 4; ++d1) { int cb = (d1 * 16 + hi * 8) * 2;
;     bf16x8 b0 = *reinterpret_cast<const bf16x8*>(Kp + KPSWZ(r32, cb));
;     bf16x8 b1 = *reinterpret_cast<const bf16x8*>(Kp + KPSWZ(32 + r32, cb));
;     p0 = __builtin_amdgcn_mfma_f32_32x32x16_bf16(b0, qr[8 + d1], p0, 0, 0, 0);
;     p1 = __builtin_amdgcn_mfma_f32_32x32x16_bf16(b1, qr[8 + d1], p1, 0, 0, 0); }
; }
	v_exp_f32_e32 v80, v80
	v_exp_f32_e32 v81, v81
	v_exp_f32_e32 v82, v82
	v_exp_f32_e32 v83, v83
	v_exp_f32_e32 v84, v84
	v_exp_f32_e32 v85, v85
	v_exp_f32_e32 v86, v86
	v_exp_f32_e32 v87, v87
	v_exp_f32_e32 v88, v88
	v_exp_f32_e32 v89, v89
	v_exp_f32_e32 v90, v90
	v_exp_f32_e32 v91, v91
	v_exp_f32_e32 v92, v92
	v_exp_f32_e32 v93, v93
	v_exp_f32_e32 v94, v94
	v_exp_f32_e32 v95, v95
	v_exp_f32_e32 v64, v64
	v_exp_f32_e32 v65, v65
	v_exp_f32_e32 v66, v66
	v_exp_f32_e32 v67, v67
	v_exp_f32_e32 v68, v68
	v_exp_f32_e32 v69, v69
	v_exp_f32_e32 v70, v70
	v_exp_f32_e32 v71, v71
	v_exp_f32_e32 v72, v72
	v_exp_f32_e32 v73, v73
	v_exp_f32_e32 v74, v74
	v_exp_f32_e32 v75, v75
	v_exp_f32_e32 v76, v76
	v_exp_f32_e32 v77, v77
	v_exp_f32_e32 v78, v78
	v_exp_f32_e32 v79, v79
	v_add_f32_e32 v249, v80, v81
	v_add_f32_e32 v250, v82, v83
	v_add_f32_e32 v251, v84, v85
	v_add_f32_e32 v182, v86, v87
	v_add_f32_e32 v249, v88, v249
	v_add_f32_e32 v250, v89, v250
	v_add_f32_e32 v251, v90, v251
	v_add_f32_e32 v182, v91, v182
	v_add_f32_e32 v249, v92, v249
	v_add_f32_e32 v250, v93, v250
	v_add_f32_e32 v251, v94, v251
	v_add_f32_e32 v182, v95, v182
	v_add_f32_e32 v249, v64, v249
	v_add_f32_e32 v250, v65, v250
	v_add_f32_e32 v251, v66, v251
	v_add_f32_e32 v182, v67, v182
	v_add_f32_e32 v249, v68, v249
	v_add_f32_e32 v250, v69, v250
	v_add_f32_e32 v251, v70, v251
	v_add_f32_e32 v182, v71, v182
	v_add_f32_e32 v249, v72, v249
	v_add_f32_e32 v250, v73, v250
	v_add_f32_e32 v251, v74, v251
	v_add_f32_e32 v182, v75, v182
	v_add_f32_e32 v249, v76, v249
	v_add_f32_e32 v250, v77, v250
	v_add_f32_e32 v251, v78, v251
	v_add_f32_e32 v182, v79, v182
	v_add_f32_e32 v249, v249, v250
	v_add_f32_e32 v251, v251, v182
	v_add_f32_e32 v249, v249, v251
	v_add_f32_e32 v176, v176, v249
	v_cvt_pk_bf16_f32 v144, v80, v81
	v_cvt_pk_bf16_f32 v145, v82, v83
	v_cvt_pk_bf16_f32 v146, v84, v85
	v_cvt_pk_bf16_f32 v147, v86, v87
	v_cvt_pk_bf16_f32 v148, v88, v89
	v_cvt_pk_bf16_f32 v149, v90, v91
	v_cvt_pk_bf16_f32 v150, v92, v93
	v_cvt_pk_bf16_f32 v151, v94, v95
	v_cvt_pk_bf16_f32 v152, v64, v65
	v_cvt_pk_bf16_f32 v153, v66, v67
	v_cvt_pk_bf16_f32 v154, v68, v69
	v_cvt_pk_bf16_f32 v155, v70, v71
	v_cvt_pk_bf16_f32 v156, v72, v73
	v_cvt_pk_bf16_f32 v157, v74, v75
	v_cvt_pk_bf16_f32 v158, v76, v77
	v_cvt_pk_bf16_f32 v159, v78, v79
.Lpp_send_Aa:
	v_add_u32_e32 v160, s73, v160
	v_add_u32_e32 v161, s73, v161
	v_add_u32_e32 v162, s73, v162
	v_add_u32_e32 v163, s73, v163
	v_add_u32_e32 v164, s73, v164
	v_add_u32_e32 v165, s73, v165
	v_add_u32_e32 v166, s73, v166
	v_add_u32_e32 v167, s73, v167
	v_add_u32_e32 v168, s74, v168
	v_add_u32_e32 v169, s74, v169
	v_add_u32_e32 v170, s74, v170
	v_add_u32_e32 v171, s74, v171
	ds_read_b128 v[192:195], v160
	ds_read_b128 v[196:199], v160 offset:8192
	ds_read_b128 v[200:203], v161
	ds_read_b128 v[204:207], v161 offset:8192
	ds_read_b128 v[208:211], v162
	ds_read_b128 v[212:215], v162 offset:8192
	ds_read_b128 v[216:219], v163
	ds_read_b128 v[220:223], v163 offset:8192
	s_waitcnt lgkmcnt(8)
	s_barrier
	s_add_i32 s11, s11, 1
	s_waitcnt lgkmcnt(6)
	v_mfma_f32_32x32x16_bf16 v[80:95], v[192:195], v[136:139], 0
	v_mfma_f32_32x32x16_bf16 v[64:79], v[196:199], v[136:139], 0
	s_add_i32 s36, s35, 3
	s_min_u32 s36, s36, 67
	s_lshl_b32 s44, s36, 6
	s_add_i32 s45, s31, s44
	s_add_i32 s46, s24, s44
	ds_read_b128 v[192:195], v164
	ds_read_b128 v[196:199], v164 offset:8192
	s_waitcnt lgkmcnt(6)
	v_mfma_f32_32x32x16_bf16 v[80:95], v[200:203], v[132:135], v[80:95]
	v_mfma_f32_32x32x16_bf16 v[64:79], v[204:207], v[132:135], v[64:79]
	s_add_i32 s46, s46, 0xffffff00
	s_cmp_lt_u32 s36, 4
	s_cselect_b32 s36, s45, s46
	s_add_i32 s37, s35, 1
	s_min_u32 s37, s37, 67
	ds_read_b128 v[200:203], v165
	ds_read_b128 v[204:207], v165 offset:8192
	s_waitcnt lgkmcnt(6)
	v_mfma_f32_32x32x16_bf16 v[80:95], v[208:211], v[128:131], v[80:95]
	v_mfma_f32_32x32x16_bf16 v[64:79], v[212:215], v[128:131], v[64:79]
	s_lshl_b32 s44, s37, 6
	s_add_i32 s45, s31, s44
	s_add_i32 s46, s24, s44
	s_add_i32 s46, s46, 0xffffff00
	s_cmp_lt_u32 s37, 4
	ds_read_b128 v[208:211], v166
	ds_read_b128 v[212:215], v166 offset:8192
	s_waitcnt lgkmcnt(6)
	v_mfma_f32_32x32x16_bf16 v[80:95], v[216:219], v[124:127], v[80:95]
	v_mfma_f32_32x32x16_bf16 v[64:79], v[220:223], v[124:127], v[64:79]
	s_cselect_b32 s37, s45, s46
	s_add_i32 s35, s35, 1
	s_lshl_b32 s44, s36, 12
	s_add_u32 s50, s47, s44
	s_addc_u32 s51, s63, 0
	ds_read_b128 v[216:219], v167
	ds_read_b128 v[220:223], v167 offset:8192
	s_waitcnt lgkmcnt(6)
	v_mfma_f32_32x32x16_bf16 v[80:95], v[192:195], v[120:123], v[80:95]
	v_mfma_f32_32x32x16_bf16 v[64:79], v[196:199], v[120:123], v[64:79]
	s_add_u32 s52, s50, 0x20000
	s_addc_u32 s53, s51, 0
	s_lshl_b32 s44, s37, 12
	s_add_u32 s54, s47, s44
	s_addc_u32 s55, s63, 0
	ds_read_b128 v[192:195], v168
	ds_read_b128 v[196:199], v168 offset:4096
	s_waitcnt lgkmcnt(6)
	v_mfma_f32_32x32x16_bf16 v[80:95], v[200:203], v[140:143], v[80:95]
	v_mfma_f32_32x32x16_bf16 v[64:79], v[204:207], v[140:143], v[64:79]
	s_add_u32 s56, s54, 0x20000
	s_addc_u32 s57, s55, 0
	s_lshl_b32 s44, s36, 10
	s_add_u32 s58, s60, s44
	s_addc_u32 s59, s61, 0
	ds_read_b128 v[200:203], v169
	ds_read_b128 v[204:207], v169 offset:4096
	s_waitcnt lgkmcnt(6)
	v_mfma_f32_32x32x16_bf16 v[80:95], v[208:211], v[116:119], v[80:95]
	v_mfma_f32_32x32x16_bf16 v[64:79], v[212:215], v[116:119], v[64:79]
	s_movk_i32 s73, 0x4000
	s_movk_i32 s74, 0x2000
	s_cmp_eq_u32 s65, 0
	s_cselect_b32 s73, s73, 0xc000
	s_cselect_b32 s74, s74, 0xa000
	ds_read_b128 v[208:211], v170
	ds_read_b128 v[212:215], v170 offset:4096
	s_waitcnt lgkmcnt(6)
; __device__ __forceinline__ void qkt(f32x16& p0, f32x16& p1, const char* Kn, const char* Kp, const bf16x8* qr, int r32, int hi) {
;   p0 = f32x16{}; p1 = f32x16{};
; #pragma unroll
;   for (int d0 = 0; d0 < 8; ++d0) { int cb = (d0 * 16 + hi * 8) * 2;
;     bf16x8 b0 = *reinterpret_cast<const bf16x8*>(Kn + KSWZ(r32, cb));
;     bf16x8 b1 = *reinterpret_cast<const bf16x8*>(Kn + KSWZ(32 + r32, cb));
;     p0 = __builtin_amdgcn_mfma_f32_32x32x16_bf16(b0, qr[d0], p0, 0, 0, 0);
;     p1 = __builtin_amdgcn_mfma_f32_32x32x16_bf16(b1, qr[d0], p1, 0, 0, 0); }
; #pragma unroll
;   for (int d1 = 0; d1 < 4; ++d1) { int cb = (d1 * 16 + hi * 8) * 2;
;     bf16x8 b0 = *reinterpret_cast<const bf16x8*>(Kp + KPSWZ(r32, cb));
;     bf16x8 b1 = *reinterpret_cast<const bf16x8*>(Kp + KPSWZ(32 + r32, cb));
;     p0 = __builtin_amdgcn_mfma_f32_32x32x16_bf16(b0, qr[8 + d1], p0, 0, 0, 0);
;     p1 = __builtin_amdgcn_mfma_f32_32x32x16_bf16(b1, qr[8 + d1], p1, 0, 0, 0); }
; }
; __device__ __forceinline__ int v_st(int k, int c) { const int kk = (k & ~0xC) | ((k & 4) << 1) | ((k & 8) >> 1); return ((kk >> 3) * 4 + (c >> 5)) * 512 + ((kk & 7) * 32 + (c & 31)) * 2; }
; __device__ __forceinline__ int v_rd_base(int lane) { return ((lane & 3) << 3) | (((lane >> 2) & 3) << 6) | (((lane >> 4) & 1) << 5) | (((lane >> 5) & 1) << 8); }
; template <int OFF> __device__ __forceinline__ s16x4 tr_read(int vb) {
;   s16x4 r; asm volatile("ds_read_b64_tr_b16 %0, %1 offset:%2" : "=&v"(r) : "v"(vb), "i"(OFF) : "memory"); return r;
; }
; template <int D0> __device__ __forceinline__ void pv_one(f32x16& od, int vb, bf16x8 pa0, bf16x8 pa1, bf16x8 pa2, bf16x8 pa3) {
;   const s16x4 l0 = tr_read<v_rd_off(D0, 0, 0)>(vb), h0 = tr_read<v_rd_off(D0, 0, 1)>(vb), l1 = tr_read<v_rd_off(D0, 1, 0)>(vb), h1 = tr_read<v_rd_off(D0, 1, 1)>(vb);
;   const s16x4 l2 = tr_read<v_rd_off(D0, 2, 0)>(vb), h2 = tr_read<v_rd_off(D0, 2, 1)>(vb), l3 = tr_read<v_rd_off(D0, 3, 0)>(vb), h3 = tr_read<v_rd_off(D0, 3, 1)>(vb);
;   asm volatile("s_waitcnt lgkmcnt(0)" ::: "memory"); SBAR();
;     ...
;   od = __builtin_amdgcn_mfma_f32_32x32x16_bf16(pa0, PK(l0, h0), od, 0, 0, 0);
;   od = __builtin_amdgcn_mfma_f32_32x32x16_bf16(pa1, PK(l1, h1), od, 0, 0, 0);
;   od = __builtin_amdgcn_mfma_f32_32x32x16_bf16(pa2, PK(l2, h2), od, 0, 0, 0);
;   od = __builtin_amdgcn_mfma_f32_32x32x16_bf16(pa3, PK(l3, h3), od, 0, 0, 0);
;     ...
; }
	v_mfma_f32_32x32x16_bf16 v[80:95], v[216:219], v[112:115], v[80:95]
	v_mfma_f32_32x32x16_bf16 v[64:79], v[220:223], v[112:115], v[64:79]
	s_cmp_eq_u32 s65, 2
	s_cselect_b32 s73, 0xffff0000, s73
	s_cselect_b32 s74, 0xffff4000, s74
	s_cselect_b32 s65, -1, s65
	s_add_i32 s65, s65, 1
	ds_read_b128 v[216:219], v171
	ds_read_b128 v[220:223], v171 offset:4096
	s_waitcnt lgkmcnt(6)
	v_mfma_f32_32x32x16_bf16 v[80:95], v[192:195], v[108:111], v[80:95]
	v_mfma_f32_32x32x16_bf16 v[64:79], v[196:199], v[108:111], v[64:79]
	s_movk_i32 s75, 0x4000
	s_movk_i32 s98, 0x2000
	s_cmp_eq_u32 s72, 0
	s_cselect_b32 s75, s75, 0xc000
	s_cselect_b32 s98, s98, 0xa000
	ds_read_b64_tr_b16 v[192:193], v174 offset:0
	ds_read_b64_tr_b16 v[194:195], v174 offset:2048
	ds_read_b64_tr_b16 v[196:197], v174 offset:4096
	ds_read_b64_tr_b16 v[198:199], v174 offset:6144
	s_waitcnt lgkmcnt(8)
	v_mfma_f32_32x32x16_bf16 v[80:95], v[200:203], v[104:107], v[80:95]
	v_mfma_f32_32x32x16_bf16 v[64:79], v[204:207], v[104:107], v[64:79]
	s_cmp_eq_u32 s72, 2
	s_cselect_b32 s75, 0xffff0000, s75
	s_cselect_b32 s98, 0xffff4000, s98
	s_cselect_b32 s72, -1, s72
	s_add_i32 s72, s72, 1
	ds_read_b64_tr_b16 v[200:201], v174 offset:8192
	ds_read_b64_tr_b16 v[202:203], v174 offset:10240
	ds_read_b64_tr_b16 v[204:205], v174 offset:12288
	ds_read_b64_tr_b16 v[206:207], v174 offset:14336
	s_waitcnt lgkmcnt(10)
	v_mfma_f32_32x32x16_bf16 v[80:95], v[208:211], v[100:103], v[80:95]
	v_mfma_f32_32x32x16_bf16 v[64:79], v[212:215], v[100:103], v[64:79]
	ds_read_b64_tr_b16 v[208:209], v174 offset:512
	ds_read_b64_tr_b16 v[210:211], v174 offset:2560
	ds_read_b64_tr_b16 v[212:213], v174 offset:4608
	ds_read_b64_tr_b16 v[214:215], v174 offset:6656
	s_waitcnt lgkmcnt(12)
	v_mfma_f32_32x32x16_bf16 v[80:95], v[216:219], v[96:99], v[80:95]
	v_mfma_f32_32x32x16_bf16 v[64:79], v[220:223], v[96:99], v[64:79]
	ds_read_b64_tr_b16 v[216:217], v174 offset:8704
	ds_read_b64_tr_b16 v[218:219], v174 offset:10752
	ds_read_b64_tr_b16 v[220:221], v174 offset:12800
	ds_read_b64_tr_b16 v[222:223], v174 offset:14848
	s_waitcnt lgkmcnt(12)
	v_mfma_f32_32x32x16_bf16 v[0:15], v[144:147], v[192:195], v[0:15]
	ds_read_b64_tr_b16 v[192:193], v174 offset:1024
	ds_read_b64_tr_b16 v[194:195], v174 offset:3072
	v_mfma_f32_32x32x16_bf16 v[0:15], v[148:151], v[196:199], v[0:15]
	ds_read_b64_tr_b16 v[196:197], v174 offset:5120
	ds_read_b64_tr_b16 v[198:199], v174 offset:7168
	s_waitcnt lgkmcnt(12)
	v_mfma_f32_32x32x16_bf16 v[0:15], v[152:155], v[200:203], v[0:15]
	ds_read_b64_tr_b16 v[200:201], v174 offset:9216
	ds_read_b64_tr_b16 v[202:203], v174 offset:11264
	v_mfma_f32_32x32x16_bf16 v[0:15], v[156:159], v[204:207], v[0:15]
	ds_read_b64_tr_b16 v[204:205], v174 offset:13312
	ds_read_b64_tr_b16 v[206:207], v174 offset:15360
	s_waitcnt lgkmcnt(12)
	v_mfma_f32_32x32x16_bf16 v[48:63], v[144:147], v[208:211], v[48:63]
	ds_read_b64_tr_b16 v[208:209], v174 offset:1536
	ds_read_b64_tr_b16 v[210:211], v174 offset:3584
	v_mfma_f32_32x32x16_bf16 v[48:63], v[148:151], v[212:215], v[48:63]
	ds_read_b64_tr_b16 v[212:213], v174 offset:5632
	ds_read_b64_tr_b16 v[214:215], v174 offset:7680
	s_waitcnt lgkmcnt(12)
	v_mfma_f32_32x32x16_bf16 v[48:63], v[152:155], v[216:219], v[48:63]
	ds_read_b64_tr_b16 v[216:217], v174 offset:9728
	ds_read_b64_tr_b16 v[218:219], v174 offset:11776
	v_mfma_f32_32x32x16_bf16 v[48:63], v[156:159], v[220:223], v[48:63]
	ds_read_b64_tr_b16 v[220:221], v174 offset:13824
	ds_read_b64_tr_b16 v[222:223], v174 offset:15872
	s_waitcnt lgkmcnt(12)
	v_mfma_f32_32x32x16_bf16 v[32:47], v[144:147], v[192:195], v[32:47]
	v_mfma_f32_32x32x16_bf16 v[32:47], v[148:151], v[196:199], v[32:47]
	s_waitcnt lgkmcnt(8)
	v_mfma_f32_32x32x16_bf16 v[32:47], v[152:155], v[200:203], v[32:47]
	v_mfma_f32_32x32x16_bf16 v[32:47], v[156:159], v[204:207], v[32:47]
	s_waitcnt lgkmcnt(4)
	v_mfma_f32_32x32x16_bf16 v[16:31], v[144:147], v[208:211], v[16:31]
	v_mfma_f32_32x32x16_bf16 v[16:31], v[148:151], v[212:215], v[16:31]
	s_waitcnt lgkmcnt(0)
	v_mfma_f32_32x32x16_bf16 v[16:31], v[152:155], v[216:219], v[16:31]
	v_mfma_f32_32x32x16_bf16 v[16:31], v[156:159], v[220:223], v[16:31]
	v_max3_f32 v250, v80, v81, v82
	v_max3_f32 v250, v250, v83, v84
	v_max3_f32 v250, v250, v85, v86
	v_max3_f32 v250, v250, v87, v88
	v_max3_f32 v250, v250, v89, v90
	v_max3_f32 v250, v250, v91, v92
	v_max3_f32 v250, v250, v93, v94
	v_max3_f32 v250, v250, v95, v64
	v_max3_f32 v250, v250, v65, v66
	v_max3_f32 v250, v250, v67, v68
	v_max3_f32 v250, v250, v69, v70
	v_max3_f32 v250, v250, v71, v72
	v_max3_f32 v250, v250, v73, v74
	v_max3_f32 v250, v250, v75, v76
	v_max3_f32 v250, v250, v77, v78
	v_max3_f32 v250, v250, v79, v79
	v_cmp_lt_f32_e64 vcc, s64, |v250|
	s_waitcnt vmcnt(0)
	ds_write_b128 v246, v[232:235]
	ds_write_b128 v246, v[236:239] offset:8192
	ds_write_b128 v248, v[240:243]
	ds_write_b128 v245, v[224:227]
	ds_write_b128 v245, v[228:231] offset:8192
	v_add_u32_e32 v246, s75, v246
	v_add_u32_e32 v248, s98, v248
	global_load_dwordx4 v[232:235], v180, s[50:51]
	global_load_dwordx4 v[236:239], v180, s[52:53]
	global_load_dwordx4 v[224:227], v180, s[54:55] offset:256
	global_load_dwordx4 v[228:231], v180, s[56:57] offset:256
	global_load_dwordx4 v[240:243], v181, s[58:59]
	s_cmp_lg_u32 s62, 0
	s_cbranch_scc1 .Lpp_safe_Ab
	s_cbranch_vccnz .Lpp_sw_Ab
; __device__ __forceinline__ void finishSM(f32x16& p0, f32x16& p1, float alpha, float& l_reg, bf16x8& pa0, bf16x8& pa1, bf16x8& pa2, bf16x8& pa3) {
;   for (int r = 0; r < 16; ++r) p1[r] = __builtin_amdgcn_exp2f(p1[r]);
;   float ps = 0; for (int r = 0; r < 16; ++r) ps += p0[r]; for (int r = 0; r < 16; ++r) ps += p1[r];
;   { auto rr = __builtin_amdgcn_permlane32_swap(__float_as_uint(ps), __float_as_uint(ps), false, false);
;     ps = __uint_as_float(rr[0]) + __uint_as_float(rr[1]); }
;   l_reg = l_reg * alpha + ps;
;     ...
;   PK4(p0, 0, pa0); PK4(p0, 8, pa1); PK4(p1, 0, pa2); PK4(p1, 8, pa3);
;     ...
; }
	v_exp_f32_e32 v80, v80
	v_exp_f32_e32 v81, v81
	v_exp_f32_e32 v82, v82
	v_exp_f32_e32 v83, v83
	v_exp_f32_e32 v84, v84
	v_exp_f32_e32 v85, v85
	v_exp_f32_e32 v86, v86
	v_exp_f32_e32 v87, v87
	v_exp_f32_e32 v88, v88
	v_exp_f32_e32 v89, v89
	v_exp_f32_e32 v90, v90
	v_exp_f32_e32 v91, v91
	v_exp_f32_e32 v92, v92
	v_exp_f32_e32 v93, v93
	v_exp_f32_e32 v94, v94
	v_exp_f32_e32 v95, v95
	v_exp_f32_e32 v64, v64
	v_exp_f32_e32 v65, v65
	v_exp_f32_e32 v66, v66
	v_exp_f32_e32 v67, v67
	v_exp_f32_e32 v68, v68
	v_exp_f32_e32 v69, v69
	v_exp_f32_e32 v70, v70
	v_exp_f32_e32 v71, v71
	v_exp_f32_e32 v72, v72
	v_exp_f32_e32 v73, v73
	v_exp_f32_e32 v74, v74
	v_exp_f32_e32 v75, v75
	v_exp_f32_e32 v76, v76
	v_exp_f32_e32 v77, v77
	v_exp_f32_e32 v78, v78
	v_exp_f32_e32 v79, v79
	v_add_f32_e32 v249, v80, v81
	v_add_f32_e32 v250, v82, v83
	v_add_f32_e32 v251, v84, v85
	v_add_f32_e32 v182, v86, v87
	v_add_f32_e32 v249, v88, v249
	v_add_f32_e32 v250, v89, v250
	v_add_f32_e32 v251, v90, v251
	v_add_f32_e32 v182, v91, v182
	v_add_f32_e32 v249, v92, v249
	v_add_f32_e32 v250, v93, v250
	v_add_f32_e32 v251, v94, v251
	v_add_f32_e32 v182, v95, v182
	v_add_f32_e32 v249, v64, v249
	v_add_f32_e32 v250, v65, v250
	v_add_f32_e32 v251, v66, v251
	v_add_f32_e32 v182, v67, v182
	v_add_f32_e32 v249, v68, v249
	v_add_f32_e32 v250, v69, v250
	v_add_f32_e32 v251, v70, v251
	v_add_f32_e32 v182, v71, v182
	v_add_f32_e32 v249, v72, v249
	v_add_f32_e32 v250, v73, v250
	v_add_f32_e32 v251, v74, v251
	v_add_f32_e32 v182, v75, v182
	v_add_f32_e32 v249, v76, v249
	v_add_f32_e32 v250, v77, v250
	v_add_f32_e32 v251, v78, v251
	v_add_f32_e32 v182, v79, v182
	v_add_f32_e32 v249, v249, v250
	v_add_f32_e32 v251, v251, v182
	v_add_f32_e32 v249, v249, v251
	v_add_f32_e32 v176, v176, v249
	v_cvt_pk_bf16_f32 v144, v80, v81
	v_cvt_pk_bf16_f32 v145, v82, v83
	v_cvt_pk_bf16_f32 v146, v84, v85
	v_cvt_pk_bf16_f32 v147, v86, v87
	v_cvt_pk_bf16_f32 v148, v88, v89
	v_cvt_pk_bf16_f32 v149, v90, v91
	v_cvt_pk_bf16_f32 v150, v92, v93
	v_cvt_pk_bf16_f32 v151, v94, v95
	v_cvt_pk_bf16_f32 v152, v64, v65
	v_cvt_pk_bf16_f32 v153, v66, v67
	v_cvt_pk_bf16_f32 v154, v68, v69
	v_cvt_pk_bf16_f32 v155, v70, v71
	v_cvt_pk_bf16_f32 v156, v72, v73
	v_cvt_pk_bf16_f32 v157, v74, v75
	v_cvt_pk_bf16_f32 v158, v76, v77
	v_cvt_pk_bf16_f32 v159, v78, v79
.Lpp_send_Ab:
	v_add_u32_e32 v160, s73, v160
	v_add_u32_e32 v161, s73, v161
	v_add_u32_e32 v162, s73, v162
	v_add_u32_e32 v163, s73, v163
	v_add_u32_e32 v164, s73, v164
	v_add_u32_e32 v165, s73, v165
	v_add_u32_e32 v166, s73, v166
	v_add_u32_e32 v167, s73, v167
	v_add_u32_e32 v168, s74, v168
	v_add_u32_e32 v169, s74, v169
	v_add_u32_e32 v170, s74, v170
	v_add_u32_e32 v171, s74, v171
	ds_read_b128 v[192:195], v160
	ds_read_b128 v[196:199], v160 offset:8192
	ds_read_b128 v[200:203], v161
	ds_read_b128 v[204:207], v161 offset:8192
	ds_read_b128 v[208:211], v162
	ds_read_b128 v[212:215], v162 offset:8192
	ds_read_b128 v[216:219], v163
	ds_read_b128 v[220:223], v163 offset:8192
	s_waitcnt lgkmcnt(8)
	s_barrier
	s_add_i32 s11, s11, 1
	s_cmp_eq_u32 s11, 68
	s_cbranch_scc1 .Lpp_alast
; __device__ __forceinline__ void qkt(f32x16& p0, f32x16& p1, const char* Kn, const char* Kp, const bf16x8* qr, int r32, int hi) {
;   p0 = f32x16{}; p1 = f32x16{};
; #pragma unroll
;   for (int d0 = 0; d0 < 8; ++d0) { int cb = (d0 * 16 + hi * 8) * 2;
;     bf16x8 b0 = *reinterpret_cast<const bf16x8*>(Kn + KSWZ(r32, cb));
;     bf16x8 b1 = *reinterpret_cast<const bf16x8*>(Kn + KSWZ(32 + r32, cb));
;     p0 = __builtin_amdgcn_mfma_f32_32x32x16_bf16(b0, qr[d0], p0, 0, 0, 0);
;     p1 = __builtin_amdgcn_mfma_f32_32x32x16_bf16(b1, qr[d0], p1, 0, 0, 0); }
; #pragma unroll
;   for (int d1 = 0; d1 < 4; ++d1) { int cb = (d1 * 16 + hi * 8) * 2;
;     bf16x8 b0 = *reinterpret_cast<const bf16x8*>(Kp + KPSWZ(r32, cb));
;     bf16x8 b1 = *reinterpret_cast<const bf16x8*>(Kp + KPSWZ(32 + r32, cb));
;     p0 = __builtin_amdgcn_mfma_f32_32x32x16_bf16(b0, qr[8 + d1], p0, 0, 0, 0);
;     p1 = __builtin_amdgcn_mfma_f32_32x32x16_bf16(b1, qr[8 + d1], p1, 0, 0, 0); }
; }
; __device__ __forceinline__ int v_st(int k, int c) { const int kk = (k & ~0xC) | ((k & 4) << 1) | ((k & 8) >> 1); return ((kk >> 3) * 4 + (c >> 5)) * 512 + ((kk & 7) * 32 + (c & 31)) * 2; }
; __device__ __forceinline__ int v_rd_base(int lane) { return ((lane & 3) << 3) | (((lane >> 2) & 3) << 6) | (((lane >> 4) & 1) << 5) | (((lane >> 5) & 1) << 8); }
; template <int OFF> __device__ __forceinline__ s16x4 tr_read(int vb) {
;   s16x4 r; asm volatile("ds_read_b64_tr_b16 %0, %1 offset:%2" : "=&v"(r) : "v"(vb), "i"(OFF) : "memory"); return r;
; }
; template <int D0> __device__ __forceinline__ void pv_one(f32x16& od, int vb, bf16x8 pa0, bf16x8 pa1, bf16x8 pa2, bf16x8 pa3) {
;   const s16x4 l0 = tr_read<v_rd_off(D0, 0, 0)>(vb), h0 = tr_read<v_rd_off(D0, 0, 1)>(vb), l1 = tr_read<v_rd_off(D0, 1, 0)>(vb), h1 = tr_read<v_rd_off(D0, 1, 1)>(vb);
;   const s16x4 l2 = tr_read<v_rd_off(D0, 2, 0)>(vb), h2 = tr_read<v_rd_off(D0, 2, 1)>(vb), l3 = tr_read<v_rd_off(D0, 3, 0)>(vb), h3 = tr_read<v_rd_off(D0, 3, 1)>(vb);
;   asm volatile("s_waitcnt lgkmcnt(0)" ::: "memory"); SBAR();
;     ...
;   od = __builtin_amdgcn_mfma_f32_32x32x16_bf16(pa0, PK(l0, h0), od, 0, 0, 0);
;   od = __builtin_amdgcn_mfma_f32_32x32x16_bf16(pa1, PK(l1, h1), od, 0, 0, 0);
;   od = __builtin_amdgcn_mfma_f32_32x32x16_bf16(pa2, PK(l2, h2), od, 0, 0, 0);
;   od = __builtin_amdgcn_mfma_f32_32x32x16_bf16(pa3, PK(l3, h3), od, 0, 0, 0);
;     ...
; }
	s_waitcnt lgkmcnt(6)
	v_mfma_f32_32x32x16_bf16 v[80:95], v[192:195], v[136:139], 0
	v_mfma_f32_32x32x16_bf16 v[64:79], v[196:199], v[136:139], 0
	s_add_i32 s36, s35, 3
	s_min_u32 s36, s36, 67
	s_lshl_b32 s44, s36, 6
	s_add_i32 s45, s31, s44
	s_add_i32 s46, s24, s44
	ds_read_b128 v[192:195], v164
	ds_read_b128 v[196:199], v164 offset:8192
	s_waitcnt lgkmcnt(6)
	v_mfma_f32_32x32x16_bf16 v[80:95], v[200:203], v[132:135], v[80:95]
	v_mfma_f32_32x32x16_bf16 v[64:79], v[204:207], v[132:135], v[64:79]
	s_add_i32 s46, s46, 0xffffff00
	s_cmp_lt_u32 s36, 4
	s_cselect_b32 s36, s45, s46
	s_add_i32 s37, s35, 1
	s_min_u32 s37, s37, 67
	ds_read_b128 v[200:203], v165
	ds_read_b128 v[204:207], v165 offset:8192
	s_waitcnt lgkmcnt(6)
	v_mfma_f32_32x32x16_bf16 v[80:95], v[208:211], v[128:131], v[80:95]
	v_mfma_f32_32x32x16_bf16 v[64:79], v[212:215], v[128:131], v[64:79]
	s_lshl_b32 s44, s37, 6
	s_add_i32 s45, s31, s44
	s_add_i32 s46, s24, s44
	s_add_i32 s46, s46, 0xffffff00
	s_cmp_lt_u32 s37, 4
	ds_read_b128 v[208:211], v166
	ds_read_b128 v[212:215], v166 offset:8192
	s_waitcnt lgkmcnt(6)
	v_mfma_f32_32x32x16_bf16 v[80:95], v[216:219], v[124:127], v[80:95]
	v_mfma_f32_32x32x16_bf16 v[64:79], v[220:223], v[124:127], v[64:79]
	s_cselect_b32 s37, s45, s46
	s_add_i32 s35, s35, 1
	s_lshl_b32 s44, s36, 12
	s_add_u32 s50, s47, s44
	s_addc_u32 s51, s63, 0
	ds_read_b128 v[216:219], v167
	ds_read_b128 v[220:223], v167 offset:8192
	s_waitcnt lgkmcnt(6)
	v_mfma_f32_32x32x16_bf16 v[80:95], v[192:195], v[120:123], v[80:95]
	v_mfma_f32_32x32x16_bf16 v[64:79], v[196:199], v[120:123], v[64:79]
	s_add_u32 s52, s50, 0x20000
	s_addc_u32 s53, s51, 0
	s_lshl_b32 s44, s37, 12
	s_add_u32 s54, s47, s44
	s_addc_u32 s55, s63, 0
	ds_read_b128 v[192:195], v168
	ds_read_b128 v[196:199], v168 offset:4096
	s_waitcnt lgkmcnt(6)
	v_mfma_f32_32x32x16_bf16 v[80:95], v[200:203], v[140:143], v[80:95]
	v_mfma_f32_32x32x16_bf16 v[64:79], v[204:207], v[140:143], v[64:79]
	s_add_u32 s56, s54, 0x20000
	s_addc_u32 s57, s55, 0
	s_lshl_b32 s44, s36, 10
	s_add_u32 s58, s60, s44
	s_addc_u32 s59, s61, 0
	ds_read_b128 v[200:203], v169
	ds_read_b128 v[204:207], v169 offset:4096
	s_waitcnt lgkmcnt(6)
	v_mfma_f32_32x32x16_bf16 v[80:95], v[208:211], v[116:119], v[80:95]
	v_mfma_f32_32x32x16_bf16 v[64:79], v[212:215], v[116:119], v[64:79]
	s_movk_i32 s73, 0x4000
	s_movk_i32 s74, 0x2000
	s_cmp_eq_u32 s65, 0
	s_cselect_b32 s73, s73, 0xc000
	s_cselect_b32 s74, s74, 0xa000
	ds_read_b128 v[208:211], v170
	ds_read_b128 v[212:215], v170 offset:4096
	s_waitcnt lgkmcnt(6)
	v_mfma_f32_32x32x16_bf16 v[80:95], v[216:219], v[112:115], v[80:95]
	v_mfma_f32_32x32x16_bf16 v[64:79], v[220:223], v[112:115], v[64:79]
	s_cmp_eq_u32 s65, 2
	s_cselect_b32 s73, 0xffff0000, s73
	s_cselect_b32 s74, 0xffff4000, s74
	s_cselect_b32 s65, -1, s65
	s_add_i32 s65, s65, 1
	ds_read_b128 v[216:219], v171
	ds_read_b128 v[220:223], v171 offset:4096
	s_waitcnt lgkmcnt(6)
	v_mfma_f32_32x32x16_bf16 v[80:95], v[192:195], v[108:111], v[80:95]
	v_mfma_f32_32x32x16_bf16 v[64:79], v[196:199], v[108:111], v[64:79]
	s_movk_i32 s75, 0x4000
	s_movk_i32 s98, 0x2000
	s_cmp_eq_u32 s72, 0
	s_cselect_b32 s75, s75, 0xc000
	s_cselect_b32 s98, s98, 0xa000
	ds_read_b64_tr_b16 v[192:193], v174 offset:16384
	ds_read_b64_tr_b16 v[194:195], v174 offset:18432
	ds_read_b64_tr_b16 v[196:197], v174 offset:20480
	ds_read_b64_tr_b16 v[198:199], v174 offset:22528
	s_waitcnt lgkmcnt(8)
	v_mfma_f32_32x32x16_bf16 v[80:95], v[200:203], v[104:107], v[80:95]
	v_mfma_f32_32x32x16_bf16 v[64:79], v[204:207], v[104:107], v[64:79]
	s_cmp_eq_u32 s72, 2
	s_cselect_b32 s75, 0xffff0000, s75
	s_cselect_b32 s98, 0xffff4000, s98
	s_cselect_b32 s72, -1, s72
	s_add_i32 s72, s72, 1
	ds_read_b64_tr_b16 v[200:201], v174 offset:24576
	ds_read_b64_tr_b16 v[202:203], v174 offset:26624
	ds_read_b64_tr_b16 v[204:205], v174 offset:28672
	ds_read_b64_tr_b16 v[206:207], v174 offset:30720
	s_waitcnt lgkmcnt(10)
	v_mfma_f32_32x32x16_bf16 v[80:95], v[208:211], v[100:103], v[80:95]
	v_mfma_f32_32x32x16_bf16 v[64:79], v[212:215], v[100:103], v[64:79]
	ds_read_b64_tr_b16 v[208:209], v174 offset:16896
	ds_read_b64_tr_b16 v[210:211], v174 offset:18944
	ds_read_b64_tr_b16 v[212:213], v174 offset:20992
	ds_read_b64_tr_b16 v[214:215], v174 offset:23040
	s_waitcnt lgkmcnt(12)
	v_mfma_f32_32x32x16_bf16 v[80:95], v[216:219], v[96:99], v[80:95]
	v_mfma_f32_32x32x16_bf16 v[64:79], v[220:223], v[96:99], v[64:79]
	ds_read_b64_tr_b16 v[216:217], v174 offset:25088
	ds_read_b64_tr_b16 v[218:219], v174 offset:27136
	ds_read_b64_tr_b16 v[220:221], v174 offset:29184
	ds_read_b64_tr_b16 v[222:223], v174 offset:31232
	s_waitcnt lgkmcnt(12)
	v_mfma_f32_32x32x16_bf16 v[0:15], v[144:147], v[192:195], v[0:15]
	ds_read_b64_tr_b16 v[192:193], v174 offset:17408
	ds_read_b64_tr_b16 v[194:195], v174 offset:19456
	v_mfma_f32_32x32x16_bf16 v[0:15], v[148:151], v[196:199], v[0:15]
	ds_read_b64_tr_b16 v[196:197], v174 offset:21504
	ds_read_b64_tr_b16 v[198:199], v174 offset:23552
	s_waitcnt lgkmcnt(12)
	v_mfma_f32_32x32x16_bf16 v[0:15], v[152:155], v[200:203], v[0:15]
	ds_read_b64_tr_b16 v[200:201], v174 offset:25600
	ds_read_b64_tr_b16 v[202:203], v174 offset:27648
	v_mfma_f32_32x32x16_bf16 v[0:15], v[156:159], v[204:207], v[0:15]
	ds_read_b64_tr_b16 v[204:205], v174 offset:29696
	ds_read_b64_tr_b16 v[206:207], v174 offset:31744
	s_waitcnt lgkmcnt(12)
	v_mfma_f32_32x32x16_bf16 v[48:63], v[144:147], v[208:211], v[48:63]
	ds_read_b64_tr_b16 v[208:209], v174 offset:17920
	ds_read_b64_tr_b16 v[210:211], v174 offset:19968
	v_mfma_f32_32x32x16_bf16 v[48:63], v[148:151], v[212:215], v[48:63]
	ds_read_b64_tr_b16 v[212:213], v174 offset:22016
	ds_read_b64_tr_b16 v[214:215], v174 offset:24064
	s_waitcnt lgkmcnt(12)
	v_mfma_f32_32x32x16_bf16 v[48:63], v[152:155], v[216:219], v[48:63]
	ds_read_b64_tr_b16 v[216:217], v174 offset:26112
	ds_read_b64_tr_b16 v[218:219], v174 offset:28160
	v_mfma_f32_32x32x16_bf16 v[48:63], v[156:159], v[220:223], v[48:63]
	ds_read_b64_tr_b16 v[220:221], v174 offset:30208
	ds_read_b64_tr_b16 v[222:223], v174 offset:32256
	s_waitcnt lgkmcnt(12)
	v_mfma_f32_32x32x16_bf16 v[32:47], v[144:147], v[192:195], v[32:47]
	v_mfma_f32_32x32x16_bf16 v[32:47], v[148:151], v[196:199], v[32:47]
	s_waitcnt lgkmcnt(8)
	v_mfma_f32_32x32x16_bf16 v[32:47], v[152:155], v[200:203], v[32:47]
	v_mfma_f32_32x32x16_bf16 v[32:47], v[156:159], v[204:207], v[32:47]
	s_waitcnt lgkmcnt(4)
	v_mfma_f32_32x32x16_bf16 v[16:31], v[144:147], v[208:211], v[16:31]
	v_mfma_f32_32x32x16_bf16 v[16:31], v[148:151], v[212:215], v[16:31]
	s_waitcnt lgkmcnt(0)
	v_mfma_f32_32x32x16_bf16 v[16:31], v[152:155], v[216:219], v[16:31]
	v_mfma_f32_32x32x16_bf16 v[16:31], v[156:159], v[220:223], v[16:31]
	s_branch .Lpp_aloop
